# fused residual+LayerNorm GEMM epilogue: 32 serialized base loads turned into rolling 12-16 deep pipeline with counted vmcnt (4 instances)
# speedup vs baseline: 1.0316x; 1.0098x over previous
.LBB0_939:
	v_ashrrev_i32_e32 v128, 2, v182
	v_and_b32_e32 v128, -4, v128
	v_and_b32_e32 v132, 64, v178
	v_add_u32_e32 v130, s67, v128
	v_xor_b32_e32 v128, 16, v178
	v_add_u32_e32 v132, 64, v132
	v_cmp_lt_i32_e32 vcc, v128, v132
	s_lshl_b32 s4, s6, 8
	v_ashrrev_i32_e32 v131, 31, v130
	v_cndmask_b32_e32 v128, v178, v128, vcc
	v_lshlrev_b32_e32 v184, 2, v128
	v_xor_b32_e32 v128, 32, v178
	v_cmp_lt_i32_e32 vcc, v128, v132
	s_barrier
	v_lshl_add_u32 v185, v181, 5, s75
	v_cndmask_b32_e32 v128, v178, v128, vcc
	v_lshlrev_b32_e32 v183, 2, v128
	v_add_u32_e32 v128, s4, v181
	v_lshlrev_b64 v[132:133], 13, v[128:129]
	v_lshl_add_u64 v[132:133], s[76:77], 0, v[132:133]
	v_lshl_add_u64 v[136:137], v[130:131], 2, v[132:133]
	v_mov_b64_e32 v[252:253], v[136:137]
	global_load_dwordx4 v[186:189], v[252:253], off
	global_load_dwordx4 v[190:193], v[252:253], off offset:64
	global_load_dwordx4 v[194:197], v[252:253], off offset:512
	global_load_dwordx4 v[198:201], v[252:253], off offset:576
	s_mov_b32 s98, 0x20000
	s_mov_b32 s99, 0
	v_lshl_add_u64 v[254:255], v[252:253], 0, s[98:99]
	global_load_dwordx4 v[202:205], v[254:255], off
	global_load_dwordx4 v[206:209], v[254:255], off offset:64
	global_load_dwordx4 v[210:213], v[254:255], off offset:512
	global_load_dwordx4 v[214:217], v[254:255], off offset:576
	s_mov_b32 s98, 0x40000
	s_mov_b32 s99, 0
	v_lshl_add_u64 v[254:255], v[252:253], 0, s[98:99]
	global_load_dwordx4 v[218:221], v[254:255], off
	global_load_dwordx4 v[222:225], v[254:255], off offset:64
	global_load_dwordx4 v[226:229], v[254:255], off offset:512
	global_load_dwordx4 v[230:233], v[254:255], off offset:576
	s_mov_b32 s98, 0x60000
	s_mov_b32 s99, 0
	v_lshl_add_u64 v[254:255], v[252:253], 0, s[98:99]
	global_load_dwordx4 v[234:237], v[254:255], off
	global_load_dwordx4 v[238:241], v[254:255], off offset:64
	global_load_dwordx4 v[242:245], v[254:255], off offset:512
	global_load_dwordx4 v[246:249], v[254:255], off offset:576
	v_cmp_gt_u32_e32 vcc, 16, v182
	s_waitcnt vmcnt(15)
	v_pk_fma_f32 v[126:127], v[188:189], s[66:67], v[126:127] op_sel_hi:[1,0,1]
	v_pk_fma_f32 v[124:125], v[186:187], s[66:67], v[124:125] op_sel_hi:[1,0,1]
	v_add_f32_e32 v138, v124, v125
	v_add_f32_e32 v140, v126, v127
	v_mul_f32_e32 v143, v124, v124
	v_mul_f32_e32 v145, v125, v125
	v_mul_f32_e32 v147, v126, v126
	v_mul_f32_e32 v149, v127, v127
	s_waitcnt vmcnt(14)
	v_pk_fma_f32 v[122:123], v[192:193], s[66:67], v[122:123] op_sel_hi:[1,0,1]
	v_pk_fma_f32 v[120:121], v[190:191], s[66:67], v[120:121] op_sel_hi:[1,0,1]
	v_mul_f32_e32 v132, v122, v122
	v_pk_fma_f32 v[150:151], v[122:123], v[122:123], v[132:133] op_sel_hi:[1,1,0]
	v_mul_f32_e32 v139, v120, v120
	v_mul_f32_e32 v141, v121, v121
	v_mov_b32_e32 v142, v120
	v_mov_b32_e32 v144, v121
	v_mov_b32_e32 v146, v122
	v_mov_b32_e32 v148, v123
	v_pk_add_f32 v[142:143], v[142:143], v[144:145]
	v_pk_add_f32 v[144:145], v[146:147], v[148:149]
	v_pk_add_f32 v[138:139], v[138:139], v[140:141]
	v_mov_b32_e32 v150, v129
	v_pk_add_f32 v[142:143], v[142:143], v[144:145]
	v_pk_add_f32 v[138:139], v[138:139], v[150:151]
	s_waitcnt vmcnt(13)
	v_pk_fma_f32 v[118:119], v[196:197], s[66:67], v[118:119] op_sel_hi:[1,0,1]
	v_pk_fma_f32 v[116:117], v[194:195], s[66:67], v[116:117] op_sel_hi:[1,0,1]
	v_mul_f32_e32 v153, v116, v116
	v_mul_f32_e32 v155, v117, v117
	v_mul_f32_e32 v157, v118, v118
	v_mul_f32_e32 v159, v119, v119
	v_mov_b32_e32 v152, v116
	v_mov_b32_e32 v154, v117
	v_mov_b32_e32 v156, v118
	v_mov_b32_e32 v158, v119
	v_pk_add_f32 v[138:139], v[142:143], v[138:139]
	v_pk_add_f32 v[140:141], v[152:153], v[154:155]
	v_pk_add_f32 v[142:143], v[156:157], v[158:159]
	s_waitcnt vmcnt(12)
	v_pk_fma_f32 v[134:135], v[200:201], s[66:67], v[114:115] op_sel_hi:[1,0,1]
	v_pk_fma_f32 v[132:133], v[198:199], s[66:67], v[112:113] op_sel_hi:[1,0,1]
	s_mov_b32 s98, 0x100000
	s_mov_b32 s99, 0
	v_lshl_add_u64 v[254:255], v[252:253], 0, s[98:99]
	global_load_dwordx4 v[186:189], v[254:255], off
	global_load_dwordx4 v[190:193], v[254:255], off offset:64
	global_load_dwordx4 v[194:197], v[254:255], off offset:512
	global_load_dwordx4 v[198:201], v[254:255], off offset:576
	v_mul_f32_e32 v137, v134, v134
	v_mul_f32_e32 v113, v132, v132
	v_mul_f32_e32 v115, v133, v133
	v_mul_f32_e32 v161, v135, v135
	v_mov_b32_e32 v112, v132
	v_mov_b32_e32 v114, v133
	v_mov_b32_e32 v136, v134
	v_mov_b32_e32 v160, v135
	v_pk_add_f32 v[140:141], v[140:141], v[142:143]
	v_pk_add_f32 v[112:113], v[112:113], v[114:115]
	v_pk_add_f32 v[114:115], v[136:137], v[160:161]
	v_pk_add_f32 v[138:139], v[138:139], v[140:141]
	v_pk_add_f32 v[112:113], v[112:113], v[114:115]
	s_nop 0
	v_pk_add_f32 v[112:113], v[138:139], v[112:113]
	ds_bpermute_b32 v114, v184, v112
	ds_bpermute_b32 v115, v184, v113
	s_waitcnt lgkmcnt(0)
	v_pk_add_f32 v[112:113], v[112:113], v[114:115]
	ds_bpermute_b32 v114, v183, v112
	ds_bpermute_b32 v115, v183, v113
	s_and_saveexec_b64 s[0:1], vcc
	s_cbranch_execz .LBB0_941
	s_waitcnt lgkmcnt(0)
	v_pk_add_f32 v[112:113], v[112:113], v[114:115]
	ds_write_b64 v185, v[112:113]
.LBB0_941:
	s_or_b64 exec, exec, s[0:1]
	v_or_b32_e32 v138, 16, v181
	s_waitcnt lgkmcnt(1)
	v_add_u32_e32 v114, s4, v138
	s_waitcnt lgkmcnt(0)
	v_mov_b32_e32 v115, v129
	v_lshlrev_b64 v[112:113], 13, v[114:115]
	v_lshl_add_u64 v[112:113], s[76:77], 0, v[112:113]
	v_lshl_add_u64 v[112:113], v[130:131], 2, v[112:113]
	s_waitcnt vmcnt(15)
	v_pk_fma_f32 v[110:111], v[204:205], s[66:67], v[110:111] op_sel_hi:[1,0,1]
	v_pk_fma_f32 v[108:109], v[202:203], s[66:67], v[108:109] op_sel_hi:[1,0,1]
	v_add_f32_e32 v136, v108, v109
	v_add_f32_e32 v144, v110, v111
	v_mul_f32_e32 v147, v108, v108
	v_mul_f32_e32 v149, v109, v109
	v_mul_f32_e32 v151, v110, v110
	v_mul_f32_e32 v153, v111, v111
	s_waitcnt vmcnt(14)
	v_pk_fma_f32 v[106:107], v[208:209], s[66:67], v[106:107] op_sel_hi:[1,0,1]
	v_pk_fma_f32 v[104:105], v[206:207], s[66:67], v[104:105] op_sel_hi:[1,0,1]
	v_mul_f32_e32 v140, v106, v106
	v_pk_fma_f32 v[154:155], v[106:107], v[106:107], v[140:141] op_sel_hi:[1,1,0]
	v_mul_f32_e32 v137, v104, v104
	v_mul_f32_e32 v145, v105, v105
	v_mov_b32_e32 v146, v104
	v_mov_b32_e32 v148, v105
	v_mov_b32_e32 v150, v106
	v_mov_b32_e32 v152, v107
	v_pk_add_f32 v[146:147], v[146:147], v[148:149]
	v_pk_add_f32 v[148:149], v[150:151], v[152:153]
	v_pk_add_f32 v[136:137], v[136:137], v[144:145]
	v_mov_b32_e32 v154, v129
	v_pk_add_f32 v[146:147], v[146:147], v[148:149]
	v_pk_add_f32 v[136:137], v[136:137], v[154:155]
	s_waitcnt vmcnt(13)
	v_pk_fma_f32 v[102:103], v[212:213], s[66:67], v[102:103] op_sel_hi:[1,0,1]
	v_pk_fma_f32 v[100:101], v[210:211], s[66:67], v[100:101] op_sel_hi:[1,0,1]
	v_mul_f32_e32 v157, v100, v100
	v_mul_f32_e32 v159, v101, v101
	v_mul_f32_e32 v161, v102, v102
	v_mul_f32_e32 v163, v103, v103
	v_mov_b32_e32 v156, v100
	v_mov_b32_e32 v158, v101
	v_mov_b32_e32 v160, v102
	v_mov_b32_e32 v162, v103
	v_pk_add_f32 v[136:137], v[146:147], v[136:137]
	v_pk_add_f32 v[144:145], v[156:157], v[158:159]
	v_pk_add_f32 v[146:147], v[160:161], v[162:163]
	s_waitcnt vmcnt(12)
	v_pk_fma_f32 v[98:99], v[216:217], s[66:67], v[98:99] op_sel_hi:[1,0,1]
	v_pk_fma_f32 v[96:97], v[214:215], s[66:67], v[96:97] op_sel_hi:[1,0,1]
	s_mov_b32 s98, 0x120000
	s_mov_b32 s99, 0
	v_lshl_add_u64 v[254:255], v[252:253], 0, s[98:99]
	global_load_dwordx4 v[202:205], v[254:255], off
	global_load_dwordx4 v[206:209], v[254:255], off offset:64
	global_load_dwordx4 v[210:213], v[254:255], off offset:512
	global_load_dwordx4 v[214:217], v[254:255], off offset:576
	v_mul_f32_e32 v143, v98, v98
	v_mul_f32_e32 v113, v96, v96
	v_mul_f32_e32 v141, v97, v97
	v_mul_f32_e32 v165, v99, v99
	v_mov_b32_e32 v112, v96
	v_mov_b32_e32 v140, v97
	v_mov_b32_e32 v142, v98
	v_mov_b32_e32 v164, v99
	v_pk_add_f32 v[144:145], v[144:145], v[146:147]
	v_pk_add_f32 v[112:113], v[112:113], v[140:141]
	v_pk_add_f32 v[140:141], v[142:143], v[164:165]
	v_pk_add_f32 v[136:137], v[136:137], v[144:145]
	v_pk_add_f32 v[112:113], v[112:113], v[140:141]
	s_nop 0
	v_pk_add_f32 v[112:113], v[136:137], v[112:113]
	ds_bpermute_b32 v136, v184, v112
	ds_bpermute_b32 v137, v184, v113
	s_waitcnt lgkmcnt(0)
	v_pk_add_f32 v[112:113], v[112:113], v[136:137]
	ds_bpermute_b32 v136, v183, v112
	ds_bpermute_b32 v137, v183, v113
	s_and_saveexec_b64 s[0:1], vcc
	s_cbranch_execz .LBB0_943
	s_waitcnt lgkmcnt(0)
	v_pk_add_f32 v[112:113], v[112:113], v[136:137]
	v_lshl_add_u32 v136, v138, 5, s75
	ds_write_b64 v136, v[112:113]
.LBB0_943:
	s_or_b64 exec, exec, s[0:1]
	v_or_b32_e32 v140, 32, v181
	v_add_u32_e32 v112, s4, v140
	v_mov_b32_e32 v113, v129
	s_waitcnt lgkmcnt(0)
	v_lshlrev_b64 v[136:137], 13, v[112:113]
	v_lshl_add_u64 v[136:137], s[76:77], 0, v[136:137]
	v_lshl_add_u64 v[142:143], v[130:131], 2, v[136:137]
	s_waitcnt vmcnt(15)
	v_pk_fma_f32 v[94:95], v[220:221], s[66:67], v[94:95] op_sel_hi:[1,0,1]
	v_pk_fma_f32 v[92:93], v[218:219], s[66:67], v[92:93] op_sel_hi:[1,0,1]
	v_add_f32_e32 v144, v92, v93
	v_add_f32_e32 v146, v94, v95
	v_mul_f32_e32 v149, v92, v92
	v_mul_f32_e32 v151, v93, v93
	v_mul_f32_e32 v153, v94, v94
	v_mul_f32_e32 v155, v95, v95
	s_waitcnt vmcnt(14)
	v_pk_fma_f32 v[90:91], v[224:225], s[66:67], v[90:91] op_sel_hi:[1,0,1]
	v_pk_fma_f32 v[88:89], v[222:223], s[66:67], v[88:89] op_sel_hi:[1,0,1]
	v_mul_f32_e32 v136, v90, v90
	v_pk_fma_f32 v[156:157], v[90:91], v[90:91], v[136:137] op_sel_hi:[1,1,0]
	v_mul_f32_e32 v145, v88, v88
	v_mul_f32_e32 v147, v89, v89
	v_mov_b32_e32 v148, v88
	v_mov_b32_e32 v150, v89
	v_mov_b32_e32 v152, v90
	v_mov_b32_e32 v154, v91
	v_pk_add_f32 v[148:149], v[148:149], v[150:151]
	v_pk_add_f32 v[150:151], v[152:153], v[154:155]
	v_pk_add_f32 v[144:145], v[144:145], v[146:147]
	v_mov_b32_e32 v156, v129
	v_pk_add_f32 v[148:149], v[148:149], v[150:151]
	v_pk_add_f32 v[144:145], v[144:145], v[156:157]
	s_waitcnt vmcnt(13)
	v_pk_fma_f32 v[86:87], v[228:229], s[66:67], v[86:87] op_sel_hi:[1,0,1]
	v_pk_fma_f32 v[84:85], v[226:227], s[66:67], v[84:85] op_sel_hi:[1,0,1]
	v_mul_f32_e32 v159, v84, v84
	v_mul_f32_e32 v161, v85, v85
	v_mul_f32_e32 v163, v86, v86
	v_mul_f32_e32 v165, v87, v87
	v_mov_b32_e32 v158, v84
	v_mov_b32_e32 v160, v85
	v_mov_b32_e32 v162, v86
	v_mov_b32_e32 v164, v87
	v_pk_add_f32 v[144:145], v[148:149], v[144:145]
	v_pk_add_f32 v[146:147], v[158:159], v[160:161]
	v_pk_add_f32 v[148:149], v[162:163], v[164:165]
	s_waitcnt vmcnt(12)
	v_pk_fma_f32 v[82:83], v[232:233], s[66:67], v[82:83] op_sel_hi:[1,0,1]
	v_pk_fma_f32 v[80:81], v[230:231], s[66:67], v[80:81] op_sel_hi:[1,0,1]
	s_mov_b32 s98, 0x140000
	s_mov_b32 s99, 0
	v_lshl_add_u64 v[254:255], v[252:253], 0, s[98:99]
	global_load_dwordx4 v[218:221], v[254:255], off
	global_load_dwordx4 v[222:225], v[254:255], off offset:64
	global_load_dwordx4 v[226:229], v[254:255], off offset:512
	global_load_dwordx4 v[230:233], v[254:255], off offset:576
	v_mul_f32_e32 v143, v82, v82
	v_mul_f32_e32 v137, v80, v80
	v_mul_f32_e32 v139, v81, v81
	v_mul_f32_e32 v167, v83, v83
	v_mov_b32_e32 v136, v80
	v_mov_b32_e32 v138, v81
	v_mov_b32_e32 v142, v82
	v_mov_b32_e32 v166, v83
	v_pk_add_f32 v[146:147], v[146:147], v[148:149]
	v_pk_add_f32 v[136:137], v[136:137], v[138:139]
	v_pk_add_f32 v[138:139], v[142:143], v[166:167]
	v_pk_add_f32 v[144:145], v[144:145], v[146:147]
	v_pk_add_f32 v[136:137], v[136:137], v[138:139]
	s_nop 0
	v_pk_add_f32 v[136:137], v[144:145], v[136:137]
	ds_bpermute_b32 v138, v184, v136
	ds_bpermute_b32 v139, v184, v137
	s_waitcnt lgkmcnt(0)
	v_pk_add_f32 v[136:137], v[136:137], v[138:139]
	ds_bpermute_b32 v138, v183, v136
	ds_bpermute_b32 v139, v183, v137
	s_and_saveexec_b64 s[0:1], vcc
	s_cbranch_execz .LBB0_945
	s_waitcnt lgkmcnt(0)
	v_pk_add_f32 v[136:137], v[136:137], v[138:139]
	v_lshl_add_u32 v138, v140, 5, s75
	ds_write_b64 v138, v[136:137]
.LBB0_945:
	s_or_b64 exec, exec, s[0:1]
	v_or_b32_e32 v142, 48, v181
	v_add_u32_e32 v136, s4, v142
	v_mov_b32_e32 v137, v129
	s_waitcnt lgkmcnt(0)
	v_lshlrev_b64 v[138:139], 13, v[136:137]
	v_lshl_add_u64 v[138:139], s[76:77], 0, v[138:139]
	v_lshl_add_u64 v[144:145], v[130:131], 2, v[138:139]
	s_waitcnt vmcnt(15)
	v_pk_fma_f32 v[78:79], v[236:237], s[66:67], v[78:79] op_sel_hi:[1,0,1]
	v_pk_fma_f32 v[76:77], v[234:235], s[66:67], v[76:77] op_sel_hi:[1,0,1]
	v_add_f32_e32 v146, v76, v77
	v_add_f32_e32 v148, v78, v79
	v_mul_f32_e32 v151, v76, v76
	v_mul_f32_e32 v153, v77, v77
	v_mul_f32_e32 v155, v78, v78
	v_mul_f32_e32 v157, v79, v79
	s_waitcnt vmcnt(14)
	v_pk_fma_f32 v[74:75], v[240:241], s[66:67], v[74:75] op_sel_hi:[1,0,1]
	v_pk_fma_f32 v[72:73], v[238:239], s[66:67], v[72:73] op_sel_hi:[1,0,1]
	v_mul_f32_e32 v138, v74, v74
	v_pk_fma_f32 v[158:159], v[74:75], v[74:75], v[138:139] op_sel_hi:[1,1,0]
	v_mul_f32_e32 v147, v72, v72
	v_mul_f32_e32 v149, v73, v73
	v_mov_b32_e32 v150, v72
	v_mov_b32_e32 v152, v73
	v_mov_b32_e32 v154, v74
	v_mov_b32_e32 v156, v75
	v_pk_add_f32 v[150:151], v[150:151], v[152:153]
	v_pk_add_f32 v[152:153], v[154:155], v[156:157]
	v_pk_add_f32 v[146:147], v[146:147], v[148:149]
	v_mov_b32_e32 v158, v129
	v_pk_add_f32 v[150:151], v[150:151], v[152:153]
	v_pk_add_f32 v[146:147], v[146:147], v[158:159]
	s_waitcnt vmcnt(13)
	v_pk_fma_f32 v[70:71], v[244:245], s[66:67], v[70:71] op_sel_hi:[1,0,1]
	v_pk_fma_f32 v[68:69], v[242:243], s[66:67], v[68:69] op_sel_hi:[1,0,1]
	v_mul_f32_e32 v161, v68, v68
	v_mul_f32_e32 v163, v69, v69
	v_mul_f32_e32 v165, v70, v70
	v_mul_f32_e32 v167, v71, v71
	v_mov_b32_e32 v160, v68
	v_mov_b32_e32 v162, v69
	v_mov_b32_e32 v164, v70
	v_mov_b32_e32 v166, v71
	v_pk_add_f32 v[146:147], v[150:151], v[146:147]
	v_pk_add_f32 v[148:149], v[160:161], v[162:163]
	v_pk_add_f32 v[150:151], v[164:165], v[166:167]
	s_waitcnt vmcnt(12)
	v_pk_fma_f32 v[66:67], v[248:249], s[66:67], v[66:67] op_sel_hi:[1,0,1]
	v_pk_fma_f32 v[64:65], v[246:247], s[66:67], v[64:65] op_sel_hi:[1,0,1]
	s_mov_b32 s98, 0x160000
	s_mov_b32 s99, 0
	v_lshl_add_u64 v[254:255], v[252:253], 0, s[98:99]
	global_load_dwordx4 v[234:237], v[254:255], off
	global_load_dwordx4 v[238:241], v[254:255], off offset:64
	global_load_dwordx4 v[242:245], v[254:255], off offset:512
	global_load_dwordx4 v[246:249], v[254:255], off offset:576
	v_mul_f32_e32 v145, v66, v66
	v_mul_f32_e32 v139, v64, v64
	v_mul_f32_e32 v141, v65, v65
	v_mul_f32_e32 v169, v67, v67
	v_mov_b32_e32 v138, v64
	v_mov_b32_e32 v140, v65
	v_mov_b32_e32 v144, v66
	v_mov_b32_e32 v168, v67
	v_pk_add_f32 v[148:149], v[148:149], v[150:151]
	v_pk_add_f32 v[138:139], v[138:139], v[140:141]
	v_pk_add_f32 v[140:141], v[144:145], v[168:169]
	v_pk_add_f32 v[146:147], v[146:147], v[148:149]
	v_pk_add_f32 v[138:139], v[138:139], v[140:141]
	s_nop 0
	v_pk_add_f32 v[138:139], v[146:147], v[138:139]
	ds_bpermute_b32 v140, v184, v138
	ds_bpermute_b32 v141, v184, v139
	s_waitcnt lgkmcnt(0)
	v_pk_add_f32 v[138:139], v[138:139], v[140:141]
	ds_bpermute_b32 v140, v183, v138
	ds_bpermute_b32 v141, v183, v139
	s_and_saveexec_b64 s[0:1], vcc
	s_cbranch_execz .LBB0_947
	s_waitcnt lgkmcnt(0)
	v_pk_add_f32 v[138:139], v[138:139], v[140:141]
	v_lshl_add_u32 v140, v142, 5, s75
	ds_write_b64 v140, v[138:139]
.LBB0_947:
	s_or_b64 exec, exec, s[0:1]
	v_add_u32_e32 v144, 0x80, v181
	v_add_u32_e32 v138, s4, v144
	v_ashrrev_i32_e32 v139, 31, v138
	s_waitcnt lgkmcnt(0)
	v_lshlrev_b64 v[140:141], 13, v[138:139]
	v_lshl_add_u64 v[140:141], s[76:77], 0, v[140:141]
	v_lshl_add_u64 v[146:147], v[130:131], 2, v[140:141]
	s_waitcnt vmcnt(15)
	v_pk_fma_f32 v[62:63], v[188:189], s[66:67], v[62:63] op_sel_hi:[1,0,1]
	v_pk_fma_f32 v[60:61], v[186:187], s[66:67], v[60:61] op_sel_hi:[1,0,1]
	v_add_f32_e32 v148, v60, v61
	v_add_f32_e32 v150, v62, v63
	v_mul_f32_e32 v153, v60, v60
	v_mul_f32_e32 v155, v61, v61
	v_mul_f32_e32 v157, v62, v62
	v_mul_f32_e32 v159, v63, v63
	s_waitcnt vmcnt(14)
	v_pk_fma_f32 v[58:59], v[192:193], s[66:67], v[58:59] op_sel_hi:[1,0,1]
	v_pk_fma_f32 v[56:57], v[190:191], s[66:67], v[56:57] op_sel_hi:[1,0,1]
	v_mul_f32_e32 v140, v58, v58
	v_pk_fma_f32 v[160:161], v[58:59], v[58:59], v[140:141] op_sel_hi:[1,1,0]
	v_mul_f32_e32 v149, v56, v56
	v_mul_f32_e32 v151, v57, v57
	v_mov_b32_e32 v152, v56
	v_mov_b32_e32 v154, v57
	v_mov_b32_e32 v156, v58
	v_mov_b32_e32 v158, v59
	v_pk_add_f32 v[152:153], v[152:153], v[154:155]
	v_pk_add_f32 v[154:155], v[156:157], v[158:159]
	v_pk_add_f32 v[148:149], v[148:149], v[150:151]
	v_mov_b32_e32 v160, v129
	v_pk_add_f32 v[152:153], v[152:153], v[154:155]
	v_pk_add_f32 v[148:149], v[148:149], v[160:161]
	s_waitcnt vmcnt(13)
	v_pk_fma_f32 v[54:55], v[196:197], s[66:67], v[54:55] op_sel_hi:[1,0,1]
	v_pk_fma_f32 v[52:53], v[194:195], s[66:67], v[52:53] op_sel_hi:[1,0,1]
	v_mul_f32_e32 v163, v52, v52
	v_mul_f32_e32 v165, v53, v53
	v_mul_f32_e32 v167, v54, v54
	v_mul_f32_e32 v169, v55, v55
	v_mov_b32_e32 v162, v52
	v_mov_b32_e32 v164, v53
	v_mov_b32_e32 v166, v54
	v_mov_b32_e32 v168, v55
	v_pk_add_f32 v[148:149], v[152:153], v[148:149]
	v_pk_add_f32 v[150:151], v[162:163], v[164:165]
	v_pk_add_f32 v[152:153], v[166:167], v[168:169]
	s_waitcnt vmcnt(12)
	v_pk_fma_f32 v[50:51], v[200:201], s[66:67], v[50:51] op_sel_hi:[1,0,1]
	v_pk_fma_f32 v[48:49], v[198:199], s[66:67], v[48:49] op_sel_hi:[1,0,1]
	v_mul_f32_e32 v147, v50, v50
	v_mul_f32_e32 v141, v48, v48
	v_mul_f32_e32 v143, v49, v49
	v_mul_f32_e32 v171, v51, v51
	v_mov_b32_e32 v140, v48
	v_mov_b32_e32 v142, v49
	v_mov_b32_e32 v146, v50
	v_mov_b32_e32 v170, v51
	v_pk_add_f32 v[150:151], v[150:151], v[152:153]
	v_pk_add_f32 v[140:141], v[140:141], v[142:143]
	v_pk_add_f32 v[142:143], v[146:147], v[170:171]
	v_pk_add_f32 v[148:149], v[148:149], v[150:151]
	v_pk_add_f32 v[140:141], v[140:141], v[142:143]
	s_nop 0
	v_pk_add_f32 v[140:141], v[148:149], v[140:141]
	ds_bpermute_b32 v142, v184, v140
	ds_bpermute_b32 v143, v184, v141
	s_waitcnt lgkmcnt(0)
	v_pk_add_f32 v[140:141], v[140:141], v[142:143]
	ds_bpermute_b32 v142, v183, v140
	ds_bpermute_b32 v143, v183, v141
	s_and_saveexec_b64 s[0:1], vcc
	s_cbranch_execz .LBB0_949
	s_waitcnt lgkmcnt(0)
	v_pk_add_f32 v[140:141], v[140:141], v[142:143]
	v_lshl_add_u32 v142, v144, 5, s75
	ds_write_b64 v142, v[140:141]
.LBB0_949:
	s_or_b64 exec, exec, s[0:1]
	v_add_u32_e32 v140, 0x90, v128
	v_ashrrev_i32_e32 v141, 31, v140
	s_waitcnt lgkmcnt(0)
	v_lshlrev_b64 v[142:143], 13, v[140:141]
	v_lshl_add_u64 v[142:143], s[76:77], 0, v[142:143]
	v_lshl_add_u64 v[146:147], v[130:131], 2, v[142:143]
	s_waitcnt vmcnt(11)
	v_pk_fma_f32 v[46:47], v[204:205], s[66:67], v[46:47] op_sel_hi:[1,0,1]
	v_pk_fma_f32 v[44:45], v[202:203], s[66:67], v[44:45] op_sel_hi:[1,0,1]
	v_add_f32_e32 v148, v44, v45
	v_add_f32_e32 v150, v46, v47
	v_mul_f32_e32 v153, v44, v44
	v_mul_f32_e32 v155, v45, v45
	v_mul_f32_e32 v157, v46, v46
	v_mul_f32_e32 v159, v47, v47
	s_waitcnt vmcnt(10)
	v_pk_fma_f32 v[42:43], v[208:209], s[66:67], v[42:43] op_sel_hi:[1,0,1]
	v_pk_fma_f32 v[40:41], v[206:207], s[66:67], v[40:41] op_sel_hi:[1,0,1]
	v_mul_f32_e32 v142, v42, v42
	v_pk_fma_f32 v[160:161], v[42:43], v[42:43], v[142:143] op_sel_hi:[1,1,0]
	v_mul_f32_e32 v149, v40, v40
	v_mul_f32_e32 v151, v41, v41
	v_mov_b32_e32 v152, v40
	v_mov_b32_e32 v154, v41
	v_mov_b32_e32 v156, v42
	v_mov_b32_e32 v158, v43
	v_pk_add_f32 v[152:153], v[152:153], v[154:155]
	v_pk_add_f32 v[154:155], v[156:157], v[158:159]
	v_pk_add_f32 v[148:149], v[148:149], v[150:151]
	v_mov_b32_e32 v160, v129
	v_pk_add_f32 v[152:153], v[152:153], v[154:155]
	v_pk_add_f32 v[148:149], v[148:149], v[160:161]
	s_waitcnt vmcnt(9)
	v_pk_fma_f32 v[38:39], v[212:213], s[66:67], v[38:39] op_sel_hi:[1,0,1]
	v_pk_fma_f32 v[36:37], v[210:211], s[66:67], v[36:37] op_sel_hi:[1,0,1]
	v_mul_f32_e32 v163, v36, v36
	v_mul_f32_e32 v165, v37, v37
	v_mul_f32_e32 v167, v38, v38
	v_mul_f32_e32 v169, v39, v39
	v_mov_b32_e32 v162, v36
	v_mov_b32_e32 v164, v37
	v_mov_b32_e32 v166, v38
	v_mov_b32_e32 v168, v39
	v_pk_add_f32 v[148:149], v[152:153], v[148:149]
	v_pk_add_f32 v[150:151], v[162:163], v[164:165]
	v_pk_add_f32 v[152:153], v[166:167], v[168:169]
	s_waitcnt vmcnt(8)
	v_pk_fma_f32 v[34:35], v[216:217], s[66:67], v[34:35] op_sel_hi:[1,0,1]
	v_pk_fma_f32 v[32:33], v[214:215], s[66:67], v[32:33] op_sel_hi:[1,0,1]
	v_mul_f32_e32 v147, v34, v34
	v_mul_f32_e32 v143, v32, v32
	v_mul_f32_e32 v145, v33, v33
	v_mul_f32_e32 v171, v35, v35
	v_mov_b32_e32 v142, v32
	v_mov_b32_e32 v144, v33
	v_mov_b32_e32 v146, v34
	v_mov_b32_e32 v170, v35
	v_pk_add_f32 v[150:151], v[150:151], v[152:153]
	v_pk_add_f32 v[142:143], v[142:143], v[144:145]
	v_pk_add_f32 v[144:145], v[146:147], v[170:171]
	v_pk_add_f32 v[148:149], v[148:149], v[150:151]
	v_pk_add_f32 v[142:143], v[142:143], v[144:145]
	s_nop 0
	v_pk_add_f32 v[142:143], v[148:149], v[142:143]
	ds_bpermute_b32 v144, v184, v142
	ds_bpermute_b32 v145, v184, v143
	s_waitcnt lgkmcnt(0)
	v_pk_add_f32 v[142:143], v[142:143], v[144:145]
	ds_bpermute_b32 v144, v183, v142
	ds_bpermute_b32 v145, v183, v143
	s_and_saveexec_b64 s[0:1], vcc
	s_cbranch_execz .LBB0_951
	s_waitcnt lgkmcnt(0)
	v_pk_add_f32 v[142:143], v[142:143], v[144:145]
	ds_write_b64 v185, v[142:143] offset:4608
.LBB0_951:
	s_or_b64 exec, exec, s[0:1]
	v_add_u32_e32 v142, 0xa0, v128
	v_ashrrev_i32_e32 v143, 31, v142
	s_waitcnt lgkmcnt(0)
	v_lshlrev_b64 v[144:145], 13, v[142:143]
	v_lshl_add_u64 v[144:145], s[76:77], 0, v[144:145]
	v_lshl_add_u64 v[156:157], v[130:131], 2, v[144:145]
	s_waitcnt vmcnt(7)
	v_pk_fma_f32 v[146:147], v[220:221], s[66:67], v[30:31] op_sel_hi:[1,0,1]
	v_pk_fma_f32 v[144:145], v[218:219], s[66:67], v[28:29] op_sel_hi:[1,0,1]
	v_add_f32_e32 v160, v144, v145
	v_add_f32_e32 v162, v146, v147
	v_mul_f32_e32 v165, v144, v144
	v_mul_f32_e32 v167, v145, v145
	v_mul_f32_e32 v169, v146, v146
	v_mul_f32_e32 v171, v147, v147
	s_waitcnt vmcnt(6)
	v_pk_fma_f32 v[150:151], v[224:225], s[66:67], v[26:27] op_sel_hi:[1,0,1]
	v_pk_fma_f32 v[148:149], v[222:223], s[66:67], v[24:25] op_sel_hi:[1,0,1]
	v_mul_f32_e32 v24, v150, v150
	v_pk_fma_f32 v[28:29], v[150:151], v[150:151], v[24:25] op_sel_hi:[1,1,0]
	v_mul_f32_e32 v161, v148, v148
	v_mul_f32_e32 v163, v149, v149
	v_mov_b32_e32 v164, v148
	v_mov_b32_e32 v166, v149
	v_mov_b32_e32 v168, v150
	v_mov_b32_e32 v170, v151
	v_pk_add_f32 v[164:165], v[164:165], v[166:167]
	v_pk_add_f32 v[166:167], v[168:169], v[170:171]
	v_pk_add_f32 v[160:161], v[160:161], v[162:163]
	v_mov_b32_e32 v28, v129
	v_pk_add_f32 v[164:165], v[164:165], v[166:167]
	v_pk_add_f32 v[28:29], v[160:161], v[28:29]
	s_waitcnt vmcnt(5)
	v_pk_fma_f32 v[154:155], v[228:229], s[66:67], v[22:23] op_sel_hi:[1,0,1]
	v_pk_fma_f32 v[152:153], v[226:227], s[66:67], v[20:21] op_sel_hi:[1,0,1]
	v_mul_f32_e32 v25, v152, v152
	v_mul_f32_e32 v27, v153, v153
	v_mul_f32_e32 v31, v154, v154
	v_mul_f32_e32 v173, v155, v155
	v_mov_b32_e32 v24, v152
	v_mov_b32_e32 v26, v153
	v_mov_b32_e32 v30, v154
	v_mov_b32_e32 v172, v155
	v_pk_add_f32 v[24:25], v[24:25], v[26:27]
	v_pk_add_f32 v[26:27], v[30:31], v[172:173]
	v_pk_add_f32 v[28:29], v[164:165], v[28:29]
	v_pk_add_f32 v[24:25], v[24:25], v[26:27]
	s_waitcnt vmcnt(4)
	v_pk_fma_f32 v[158:159], v[232:233], s[66:67], v[18:19] op_sel_hi:[1,0,1]
	v_pk_fma_f32 v[156:157], v[230:231], s[66:67], v[16:17] op_sel_hi:[1,0,1]
	v_mul_f32_e32 v21, v158, v158
	v_mul_f32_e32 v17, v156, v156
	v_mul_f32_e32 v19, v157, v157
	v_mul_f32_e32 v23, v159, v159
	v_mov_b32_e32 v16, v156
	v_mov_b32_e32 v18, v157
	v_mov_b32_e32 v20, v158
	v_mov_b32_e32 v22, v159
	v_pk_add_f32 v[16:17], v[16:17], v[18:19]
	v_pk_add_f32 v[18:19], v[20:21], v[22:23]
	v_pk_add_f32 v[24:25], v[28:29], v[24:25]
	v_pk_add_f32 v[16:17], v[16:17], v[18:19]
	s_nop 0
	v_pk_add_f32 v[16:17], v[24:25], v[16:17]
	ds_bpermute_b32 v18, v184, v16
	ds_bpermute_b32 v19, v184, v17
	s_waitcnt lgkmcnt(0)
	v_pk_add_f32 v[16:17], v[16:17], v[18:19]
	ds_bpermute_b32 v18, v183, v16
	ds_bpermute_b32 v19, v183, v17
	s_and_saveexec_b64 s[0:1], vcc
	s_cbranch_execz .LBB0_953
	s_waitcnt lgkmcnt(0)
	v_pk_add_f32 v[16:17], v[16:17], v[18:19]
	ds_write_b64 v185, v[16:17] offset:5120
.LBB0_953:
	s_or_b64 exec, exec, s[0:1]
	v_add_u32_e32 v160, 0xb0, v128
	v_ashrrev_i32_e32 v161, 31, v160
	v_lshlrev_b64 v[16:17], 13, v[160:161]
	v_lshl_add_u64 v[16:17], s[76:77], 0, v[16:17]
	v_lshl_add_u64 v[20:21], v[130:131], 2, v[16:17]
	s_waitcnt lgkmcnt(0)
	s_waitcnt vmcnt(3)
	v_pk_fma_f32 v[164:165], v[236:237], s[66:67], v[14:15] op_sel_hi:[1,0,1]
	v_pk_fma_f32 v[162:163], v[234:235], s[66:67], v[12:13] op_sel_hi:[1,0,1]
	v_add_f32_e32 v16, v162, v163
	v_add_f32_e32 v18, v164, v165
	v_mul_f32_e32 v23, v162, v162
	v_mul_f32_e32 v25, v163, v163
	v_mul_f32_e32 v27, v164, v164
	v_mul_f32_e32 v29, v165, v165
	s_waitcnt vmcnt(2)
	v_pk_fma_f32 v[168:169], v[240:241], s[66:67], v[10:11] op_sel_hi:[1,0,1]
	v_pk_fma_f32 v[166:167], v[238:239], s[66:67], v[8:9] op_sel_hi:[1,0,1]
	v_mul_f32_e32 v8, v168, v168
	v_pk_fma_f32 v[12:13], v[168:169], v[168:169], v[8:9] op_sel_hi:[1,1,0]
	v_mul_f32_e32 v17, v166, v166
	v_mul_f32_e32 v19, v167, v167
	v_mov_b32_e32 v22, v166
	v_mov_b32_e32 v24, v167
	v_mov_b32_e32 v26, v168
	v_mov_b32_e32 v28, v169
	v_pk_add_f32 v[16:17], v[16:17], v[18:19]
	v_mov_b32_e32 v12, v129
	v_pk_add_f32 v[12:13], v[16:17], v[12:13]
	s_waitcnt vmcnt(1)
	v_pk_fma_f32 v[172:173], v[244:245], s[66:67], v[6:7] op_sel_hi:[1,0,1]
	v_pk_fma_f32 v[170:171], v[242:243], s[66:67], v[4:5] op_sel_hi:[1,0,1]
	v_mul_f32_e32 v9, v170, v170
	v_mul_f32_e32 v11, v171, v171
	v_mul_f32_e32 v15, v172, v172
	v_mul_f32_e32 v31, v173, v173
	v_pk_add_f32 v[20:21], v[22:23], v[24:25]
	v_pk_add_f32 v[22:23], v[26:27], v[28:29]
	v_mov_b32_e32 v8, v170
	v_mov_b32_e32 v10, v171
	v_mov_b32_e32 v14, v172
	v_mov_b32_e32 v30, v173
	v_pk_add_f32 v[20:21], v[20:21], v[22:23]
	v_pk_add_f32 v[8:9], v[8:9], v[10:11]
	v_pk_add_f32 v[10:11], v[14:15], v[30:31]
	v_pk_add_f32 v[12:13], v[20:21], v[12:13]
	v_pk_add_f32 v[8:9], v[8:9], v[10:11]
	s_waitcnt vmcnt(0)
	v_pk_fma_f32 v[176:177], v[248:249], s[66:67], v[2:3] op_sel_hi:[1,0,1]
	v_pk_fma_f32 v[174:175], v[246:247], s[66:67], v[0:1] op_sel_hi:[1,0,1]
	v_mul_f32_e32 v5, v176, v176
	v_mul_f32_e32 v1, v174, v174
	v_mul_f32_e32 v3, v175, v175
	v_mul_f32_e32 v7, v177, v177
	v_mov_b32_e32 v0, v174
	v_mov_b32_e32 v2, v175
	v_mov_b32_e32 v4, v176
	v_mov_b32_e32 v6, v177
	v_pk_add_f32 v[0:1], v[0:1], v[2:3]
	v_pk_add_f32 v[2:3], v[4:5], v[6:7]
	v_pk_add_f32 v[8:9], v[12:13], v[8:9]
	v_pk_add_f32 v[0:1], v[0:1], v[2:3]
	s_nop 0
	v_pk_add_f32 v[0:1], v[8:9], v[0:1]
	ds_bpermute_b32 v2, v184, v0
	ds_bpermute_b32 v3, v184, v1
	s_waitcnt lgkmcnt(0)
	v_pk_add_f32 v[0:1], v[0:1], v[2:3]
	ds_bpermute_b32 v2, v183, v0
	ds_bpermute_b32 v3, v183, v1
	s_and_saveexec_b64 s[0:1], vcc
	s_cbranch_execz .LBB0_955
	s_waitcnt lgkmcnt(0)
	v_pk_add_f32 v[0:1], v[0:1], v[2:3]
	ds_write_b64 v185, v[0:1] offset:5632

.LBB0_1220:
	v_ashrrev_i32_e32 v128, 2, v198
	v_and_b32_e32 v128, -4, v128
	v_and_b32_e32 v132, 64, v194
	v_add_u32_e32 v130, s75, v128
	v_xor_b32_e32 v128, 16, v194
	v_add_u32_e32 v132, 64, v132
	v_cmp_lt_i32_e32 vcc, v128, v132
	s_lshl_b32 s4, s0, 8
	v_ashrrev_i32_e32 v131, 31, v130
	v_cndmask_b32_e32 v128, v194, v128, vcc
	v_lshlrev_b32_e32 v200, 2, v128
	v_xor_b32_e32 v128, 32, v194
	v_cmp_lt_i32_e32 vcc, v128, v132
	s_barrier
	v_lshl_add_u32 v201, v197, 5, s91
	v_cndmask_b32_e32 v128, v194, v128, vcc
	v_lshlrev_b32_e32 v199, 2, v128
	v_add_u32_e32 v128, s4, v197
	v_lshlrev_b64 v[132:133], 13, v[128:129]
	v_lshl_add_u64 v[132:133], s[68:69], 0, v[132:133]
	v_lshl_add_u64 v[132:133], v[130:131], 2, v[132:133]
	v_mov_b64_e32 v[252:253], v[132:133]
	global_load_dwordx4 v[202:205], v[252:253], off
	global_load_dwordx4 v[206:209], v[252:253], off offset:64
	global_load_dwordx4 v[210:213], v[252:253], off offset:512
	global_load_dwordx4 v[214:217], v[252:253], off offset:576
	s_mov_b32 s98, 0x20000
	s_mov_b32 s99, 0
	v_lshl_add_u64 v[254:255], v[252:253], 0, s[98:99]
	global_load_dwordx4 v[218:221], v[254:255], off
	global_load_dwordx4 v[222:225], v[254:255], off offset:64
	global_load_dwordx4 v[226:229], v[254:255], off offset:512
	global_load_dwordx4 v[230:233], v[254:255], off offset:576
	s_mov_b32 s98, 0x40000
	s_mov_b32 s99, 0
	v_lshl_add_u64 v[254:255], v[252:253], 0, s[98:99]
	global_load_dwordx4 v[234:237], v[254:255], off
	global_load_dwordx4 v[238:241], v[254:255], off offset:64
	global_load_dwordx4 v[242:245], v[254:255], off offset:512
	global_load_dwordx4 v[246:249], v[254:255], off offset:576
	v_cmp_gt_u32_e32 vcc, 16, v198
	s_waitcnt vmcnt(11)
	v_pk_fma_f32 v[126:127], v[204:205], s[90:91], v[126:127] op_sel_hi:[1,0,1]
	v_pk_fma_f32 v[124:125], v[202:203], s[90:91], v[124:125] op_sel_hi:[1,0,1]
	v_add_f32_e32 v138, v124, v125
	v_add_f32_e32 v140, v126, v127
	v_mul_f32_e32 v143, v124, v124
	v_mul_f32_e32 v145, v125, v125
	v_mul_f32_e32 v147, v126, v126
	v_mul_f32_e32 v149, v127, v127
	s_waitcnt vmcnt(10)
	v_pk_fma_f32 v[122:123], v[208:209], s[90:91], v[122:123] op_sel_hi:[1,0,1]
	v_pk_fma_f32 v[120:121], v[206:207], s[90:91], v[120:121] op_sel_hi:[1,0,1]
	v_mul_f32_e32 v134, v122, v122
	v_pk_fma_f32 v[150:151], v[122:123], v[122:123], v[134:135] op_sel_hi:[1,1,0]
	v_mul_f32_e32 v139, v120, v120
	v_mul_f32_e32 v141, v121, v121
	v_mov_b32_e32 v142, v120
	v_mov_b32_e32 v144, v121
	v_mov_b32_e32 v146, v122
	v_mov_b32_e32 v148, v123
	v_pk_add_f32 v[142:143], v[142:143], v[144:145]
	v_pk_add_f32 v[144:145], v[146:147], v[148:149]
	v_pk_add_f32 v[138:139], v[138:139], v[140:141]
	v_mov_b32_e32 v150, v129
	v_pk_add_f32 v[142:143], v[142:143], v[144:145]
	v_pk_add_f32 v[138:139], v[138:139], v[150:151]
	s_waitcnt vmcnt(9)
	v_pk_fma_f32 v[118:119], v[212:213], s[90:91], v[118:119] op_sel_hi:[1,0,1]
	v_pk_fma_f32 v[116:117], v[210:211], s[90:91], v[116:117] op_sel_hi:[1,0,1]
	v_mul_f32_e32 v153, v116, v116
	v_mul_f32_e32 v155, v117, v117
	v_mul_f32_e32 v157, v118, v118
	v_mul_f32_e32 v159, v119, v119
	v_mov_b32_e32 v152, v116
	v_mov_b32_e32 v154, v117
	v_mov_b32_e32 v156, v118
	v_mov_b32_e32 v158, v119
	v_pk_add_f32 v[138:139], v[142:143], v[138:139]
	v_pk_add_f32 v[140:141], v[152:153], v[154:155]
	v_pk_add_f32 v[142:143], v[156:157], v[158:159]
	s_waitcnt vmcnt(8)
	v_pk_fma_f32 v[114:115], v[216:217], s[90:91], v[114:115] op_sel_hi:[1,0,1]
	v_pk_fma_f32 v[112:113], v[214:215], s[90:91], v[112:113] op_sel_hi:[1,0,1]
	s_mov_b32 s98, 0x60000
	s_mov_b32 s99, 0
	v_lshl_add_u64 v[254:255], v[252:253], 0, s[98:99]
	global_load_dwordx4 v[202:205], v[254:255], off
	global_load_dwordx4 v[206:209], v[254:255], off offset:64
	global_load_dwordx4 v[210:213], v[254:255], off offset:512
	global_load_dwordx4 v[214:217], v[254:255], off offset:576
	v_mul_f32_e32 v161, v114, v114
	v_mul_f32_e32 v135, v112, v112
	v_mul_f32_e32 v137, v113, v113
	v_mul_f32_e32 v163, v115, v115
	v_mov_b32_e32 v134, v112
	v_mov_b32_e32 v136, v113
	v_mov_b32_e32 v160, v114
	v_mov_b32_e32 v162, v115
	v_pk_add_f32 v[140:141], v[140:141], v[142:143]
	v_pk_add_f32 v[134:135], v[134:135], v[136:137]
	v_pk_add_f32 v[136:137], v[160:161], v[162:163]
	v_pk_add_f32 v[138:139], v[138:139], v[140:141]
	v_pk_add_f32 v[134:135], v[134:135], v[136:137]
	s_nop 0
	v_pk_add_f32 v[134:135], v[138:139], v[134:135]
	ds_bpermute_b32 v136, v200, v134
	ds_bpermute_b32 v137, v200, v135
	s_waitcnt lgkmcnt(0)
	v_pk_add_f32 v[134:135], v[134:135], v[136:137]
	ds_bpermute_b32 v136, v199, v134
	ds_bpermute_b32 v137, v199, v135
	s_and_saveexec_b64 s[0:1], vcc
	s_cbranch_execz .LBB0_1222
	s_waitcnt lgkmcnt(0)
	v_pk_add_f32 v[134:135], v[134:135], v[136:137]
	ds_write_b64 v201, v[134:135]
.LBB0_1222:
	s_or_b64 exec, exec, s[0:1]
	v_or_b32_e32 v142, 16, v197
	s_waitcnt lgkmcnt(1)
	v_add_u32_e32 v136, s4, v142
	s_waitcnt lgkmcnt(0)
	v_mov_b32_e32 v137, v129
	v_lshlrev_b64 v[134:135], 13, v[136:137]
	v_lshl_add_u64 v[134:135], s[68:69], 0, v[134:135]
	v_lshl_add_u64 v[134:135], v[130:131], 2, v[134:135]
	s_waitcnt vmcnt(11)
	v_pk_fma_f32 v[110:111], v[220:221], s[90:91], v[110:111] op_sel_hi:[1,0,1]
	v_pk_fma_f32 v[108:109], v[218:219], s[90:91], v[108:109] op_sel_hi:[1,0,1]
	v_add_f32_e32 v144, v108, v109
	v_add_f32_e32 v146, v110, v111
	v_mul_f32_e32 v149, v108, v108
	v_mul_f32_e32 v151, v109, v109
	v_mul_f32_e32 v153, v110, v110
	v_mul_f32_e32 v155, v111, v111
	s_waitcnt vmcnt(10)
	v_pk_fma_f32 v[106:107], v[224:225], s[90:91], v[106:107] op_sel_hi:[1,0,1]
	v_pk_fma_f32 v[104:105], v[222:223], s[90:91], v[104:105] op_sel_hi:[1,0,1]
	v_mul_f32_e32 v138, v106, v106
	v_pk_fma_f32 v[156:157], v[106:107], v[106:107], v[138:139] op_sel_hi:[1,1,0]
	v_mul_f32_e32 v145, v104, v104
	v_mul_f32_e32 v147, v105, v105
	v_mov_b32_e32 v148, v104
	v_mov_b32_e32 v150, v105
	v_mov_b32_e32 v152, v106
	v_mov_b32_e32 v154, v107
	v_pk_add_f32 v[148:149], v[148:149], v[150:151]
	v_pk_add_f32 v[150:151], v[152:153], v[154:155]
	v_pk_add_f32 v[144:145], v[144:145], v[146:147]
	v_mov_b32_e32 v156, v129
	v_pk_add_f32 v[148:149], v[148:149], v[150:151]
	v_pk_add_f32 v[144:145], v[144:145], v[156:157]
	s_waitcnt vmcnt(9)
	v_pk_fma_f32 v[102:103], v[228:229], s[90:91], v[102:103] op_sel_hi:[1,0,1]
	v_pk_fma_f32 v[100:101], v[226:227], s[90:91], v[100:101] op_sel_hi:[1,0,1]
	v_mul_f32_e32 v159, v100, v100
	v_mul_f32_e32 v161, v101, v101
	v_mul_f32_e32 v163, v102, v102
	v_mul_f32_e32 v165, v103, v103
	v_mov_b32_e32 v158, v100
	v_mov_b32_e32 v160, v101
	v_mov_b32_e32 v162, v102
	v_mov_b32_e32 v164, v103
	v_pk_add_f32 v[144:145], v[148:149], v[144:145]
	v_pk_add_f32 v[146:147], v[158:159], v[160:161]
	v_pk_add_f32 v[148:149], v[162:163], v[164:165]
	s_waitcnt vmcnt(8)
	v_pk_fma_f32 v[98:99], v[232:233], s[90:91], v[98:99] op_sel_hi:[1,0,1]
	v_pk_fma_f32 v[96:97], v[230:231], s[90:91], v[96:97] op_sel_hi:[1,0,1]
	s_mov_b32 s98, 0x100000
	s_mov_b32 s99, 0
	v_lshl_add_u64 v[254:255], v[252:253], 0, s[98:99]
	global_load_dwordx4 v[218:221], v[254:255], off
	global_load_dwordx4 v[222:225], v[254:255], off offset:64
	global_load_dwordx4 v[226:229], v[254:255], off offset:512
	global_load_dwordx4 v[230:233], v[254:255], off offset:576
	v_mul_f32_e32 v167, v98, v98
	v_mul_f32_e32 v139, v96, v96
	v_mul_f32_e32 v141, v97, v97
	v_mul_f32_e32 v169, v99, v99
	v_mov_b32_e32 v138, v96
	v_mov_b32_e32 v140, v97
	v_mov_b32_e32 v166, v98
	v_mov_b32_e32 v168, v99
	v_pk_add_f32 v[146:147], v[146:147], v[148:149]
	v_pk_add_f32 v[138:139], v[138:139], v[140:141]
	v_pk_add_f32 v[140:141], v[166:167], v[168:169]
	v_pk_add_f32 v[144:145], v[144:145], v[146:147]
	v_pk_add_f32 v[138:139], v[138:139], v[140:141]
	s_nop 0
	v_pk_add_f32 v[138:139], v[144:145], v[138:139]
	ds_bpermute_b32 v140, v200, v138
	ds_bpermute_b32 v141, v200, v139
	s_waitcnt lgkmcnt(0)
	v_pk_add_f32 v[138:139], v[138:139], v[140:141]
	ds_bpermute_b32 v140, v199, v138
	ds_bpermute_b32 v141, v199, v139
	s_and_saveexec_b64 s[0:1], vcc
	s_cbranch_execz .LBB0_1224
	s_waitcnt lgkmcnt(0)
	v_pk_add_f32 v[138:139], v[138:139], v[140:141]
	v_lshl_add_u32 v140, v142, 5, s91
	ds_write_b64 v140, v[138:139]
.LBB0_1224:
	s_or_b64 exec, exec, s[0:1]
	v_or_b32_e32 v146, 32, v197
	s_waitcnt lgkmcnt(1)
	v_add_u32_e32 v140, s4, v146
	s_waitcnt lgkmcnt(0)
	v_mov_b32_e32 v141, v129
	v_lshlrev_b64 v[138:139], 13, v[140:141]
	v_lshl_add_u64 v[138:139], s[68:69], 0, v[138:139]
	v_lshl_add_u64 v[138:139], v[130:131], 2, v[138:139]
	s_waitcnt vmcnt(11)
	v_pk_fma_f32 v[94:95], v[236:237], s[90:91], v[94:95] op_sel_hi:[1,0,1]
	v_pk_fma_f32 v[92:93], v[234:235], s[90:91], v[92:93] op_sel_hi:[1,0,1]
	v_add_f32_e32 v148, v92, v93
	v_add_f32_e32 v150, v94, v95
	v_mul_f32_e32 v153, v92, v92
	v_mul_f32_e32 v155, v93, v93
	v_mul_f32_e32 v157, v94, v94
	v_mul_f32_e32 v159, v95, v95
	s_waitcnt vmcnt(10)
	v_pk_fma_f32 v[90:91], v[240:241], s[90:91], v[90:91] op_sel_hi:[1,0,1]
	v_pk_fma_f32 v[88:89], v[238:239], s[90:91], v[88:89] op_sel_hi:[1,0,1]
	v_mul_f32_e32 v142, v90, v90
	v_pk_fma_f32 v[160:161], v[90:91], v[90:91], v[142:143] op_sel_hi:[1,1,0]
	v_mul_f32_e32 v149, v88, v88
	v_mul_f32_e32 v151, v89, v89
	v_mov_b32_e32 v152, v88
	v_mov_b32_e32 v154, v89
	v_mov_b32_e32 v156, v90
	v_mov_b32_e32 v158, v91
	v_pk_add_f32 v[152:153], v[152:153], v[154:155]
	v_pk_add_f32 v[154:155], v[156:157], v[158:159]
	v_pk_add_f32 v[148:149], v[148:149], v[150:151]
	v_mov_b32_e32 v160, v129
	v_pk_add_f32 v[152:153], v[152:153], v[154:155]
	v_pk_add_f32 v[148:149], v[148:149], v[160:161]
	s_waitcnt vmcnt(9)
	v_pk_fma_f32 v[86:87], v[244:245], s[90:91], v[86:87] op_sel_hi:[1,0,1]
	v_pk_fma_f32 v[84:85], v[242:243], s[90:91], v[84:85] op_sel_hi:[1,0,1]
	v_mul_f32_e32 v163, v84, v84
	v_mul_f32_e32 v165, v85, v85
	v_mul_f32_e32 v167, v86, v86
	v_mul_f32_e32 v169, v87, v87
	v_mov_b32_e32 v162, v84
	v_mov_b32_e32 v164, v85
	v_mov_b32_e32 v166, v86
	v_mov_b32_e32 v168, v87
	v_pk_add_f32 v[148:149], v[152:153], v[148:149]
	v_pk_add_f32 v[150:151], v[162:163], v[164:165]
	v_pk_add_f32 v[152:153], v[166:167], v[168:169]
	s_waitcnt vmcnt(8)
	v_pk_fma_f32 v[82:83], v[248:249], s[90:91], v[82:83] op_sel_hi:[1,0,1]
	v_pk_fma_f32 v[80:81], v[246:247], s[90:91], v[80:81] op_sel_hi:[1,0,1]
	s_mov_b32 s98, 0x120000
	s_mov_b32 s99, 0
	v_lshl_add_u64 v[254:255], v[252:253], 0, s[98:99]
	global_load_dwordx4 v[234:237], v[254:255], off
	global_load_dwordx4 v[238:241], v[254:255], off offset:64
	global_load_dwordx4 v[242:245], v[254:255], off offset:512
	global_load_dwordx4 v[246:249], v[254:255], off offset:576
	v_mul_f32_e32 v171, v82, v82
	v_mul_f32_e32 v143, v80, v80
	v_mul_f32_e32 v145, v81, v81
	v_mul_f32_e32 v173, v83, v83
	v_mov_b32_e32 v142, v80
	v_mov_b32_e32 v144, v81
	v_mov_b32_e32 v170, v82
	v_mov_b32_e32 v172, v83
	v_pk_add_f32 v[150:151], v[150:151], v[152:153]
	v_pk_add_f32 v[142:143], v[142:143], v[144:145]
	v_pk_add_f32 v[144:145], v[170:171], v[172:173]
	v_pk_add_f32 v[148:149], v[148:149], v[150:151]
	v_pk_add_f32 v[142:143], v[142:143], v[144:145]
	s_nop 0
	v_pk_add_f32 v[142:143], v[148:149], v[142:143]
	ds_bpermute_b32 v144, v200, v142
	ds_bpermute_b32 v145, v200, v143
	s_waitcnt lgkmcnt(0)
	v_pk_add_f32 v[142:143], v[142:143], v[144:145]
	ds_bpermute_b32 v144, v199, v142
	ds_bpermute_b32 v145, v199, v143
	s_and_saveexec_b64 s[0:1], vcc
	s_cbranch_execz .LBB0_1226
	s_waitcnt lgkmcnt(0)
	v_pk_add_f32 v[142:143], v[142:143], v[144:145]
	v_lshl_add_u32 v144, v146, 5, s91
	ds_write_b64 v144, v[142:143]
.LBB0_1226:
	s_or_b64 exec, exec, s[0:1]
	v_or_b32_e32 v150, 48, v197
	s_waitcnt lgkmcnt(1)
	v_add_u32_e32 v144, s4, v150
	s_waitcnt lgkmcnt(0)
	v_mov_b32_e32 v145, v129
	v_lshlrev_b64 v[142:143], 13, v[144:145]
	v_lshl_add_u64 v[142:143], s[68:69], 0, v[142:143]
	v_lshl_add_u64 v[142:143], v[130:131], 2, v[142:143]
	s_waitcnt vmcnt(11)
	v_pk_fma_f32 v[78:79], v[204:205], s[90:91], v[78:79] op_sel_hi:[1,0,1]
	v_pk_fma_f32 v[76:77], v[202:203], s[90:91], v[76:77] op_sel_hi:[1,0,1]
	v_add_f32_e32 v152, v76, v77
	v_add_f32_e32 v154, v78, v79
	v_mul_f32_e32 v157, v76, v76
	v_mul_f32_e32 v159, v77, v77
	v_mul_f32_e32 v161, v78, v78
	v_mul_f32_e32 v163, v79, v79
	s_waitcnt vmcnt(10)
	v_pk_fma_f32 v[74:75], v[208:209], s[90:91], v[74:75] op_sel_hi:[1,0,1]
	v_pk_fma_f32 v[72:73], v[206:207], s[90:91], v[72:73] op_sel_hi:[1,0,1]
	v_mul_f32_e32 v146, v74, v74
	v_pk_fma_f32 v[164:165], v[74:75], v[74:75], v[146:147] op_sel_hi:[1,1,0]
	v_mul_f32_e32 v153, v72, v72
	v_mul_f32_e32 v155, v73, v73
	v_mov_b32_e32 v156, v72
	v_mov_b32_e32 v158, v73
	v_mov_b32_e32 v160, v74
	v_mov_b32_e32 v162, v75
	v_pk_add_f32 v[156:157], v[156:157], v[158:159]
	v_pk_add_f32 v[158:159], v[160:161], v[162:163]
	v_pk_add_f32 v[152:153], v[152:153], v[154:155]
	v_mov_b32_e32 v164, v129
	v_pk_add_f32 v[156:157], v[156:157], v[158:159]
	v_pk_add_f32 v[152:153], v[152:153], v[164:165]
	s_waitcnt vmcnt(9)
	v_pk_fma_f32 v[70:71], v[212:213], s[90:91], v[70:71] op_sel_hi:[1,0,1]
	v_pk_fma_f32 v[68:69], v[210:211], s[90:91], v[68:69] op_sel_hi:[1,0,1]
	v_mul_f32_e32 v167, v68, v68
	v_mul_f32_e32 v169, v69, v69
	v_mul_f32_e32 v171, v70, v70
	v_mul_f32_e32 v173, v71, v71
	v_mov_b32_e32 v166, v68
	v_mov_b32_e32 v168, v69
	v_mov_b32_e32 v170, v70
	v_mov_b32_e32 v172, v71
	v_pk_add_f32 v[152:153], v[156:157], v[152:153]
	v_pk_add_f32 v[154:155], v[166:167], v[168:169]
	v_pk_add_f32 v[156:157], v[170:171], v[172:173]
	s_waitcnt vmcnt(8)
	v_pk_fma_f32 v[66:67], v[216:217], s[90:91], v[66:67] op_sel_hi:[1,0,1]
	v_pk_fma_f32 v[64:65], v[214:215], s[90:91], v[64:65] op_sel_hi:[1,0,1]
	s_mov_b32 s98, 0x140000
	s_mov_b32 s99, 0
	v_lshl_add_u64 v[254:255], v[252:253], 0, s[98:99]
	global_load_dwordx4 v[202:205], v[254:255], off
	global_load_dwordx4 v[206:209], v[254:255], off offset:64
	global_load_dwordx4 v[210:213], v[254:255], off offset:512
	global_load_dwordx4 v[214:217], v[254:255], off offset:576
	v_mul_f32_e32 v175, v66, v66
	v_mul_f32_e32 v147, v64, v64
	v_mul_f32_e32 v149, v65, v65
	v_mul_f32_e32 v177, v67, v67
	v_mov_b32_e32 v146, v64
	v_mov_b32_e32 v148, v65
	v_mov_b32_e32 v174, v66
	v_mov_b32_e32 v176, v67
	v_pk_add_f32 v[154:155], v[154:155], v[156:157]
	v_pk_add_f32 v[146:147], v[146:147], v[148:149]
	v_pk_add_f32 v[148:149], v[174:175], v[176:177]
	v_pk_add_f32 v[152:153], v[152:153], v[154:155]
	v_pk_add_f32 v[146:147], v[146:147], v[148:149]
	s_nop 0
	v_pk_add_f32 v[146:147], v[152:153], v[146:147]
	ds_bpermute_b32 v148, v200, v146
	ds_bpermute_b32 v149, v200, v147
	s_waitcnt lgkmcnt(0)
	v_pk_add_f32 v[146:147], v[146:147], v[148:149]
	ds_bpermute_b32 v148, v199, v146
	ds_bpermute_b32 v149, v199, v147
	s_and_saveexec_b64 s[0:1], vcc
	s_cbranch_execz .LBB0_1228
	s_waitcnt lgkmcnt(0)
	v_pk_add_f32 v[146:147], v[146:147], v[148:149]
	v_lshl_add_u32 v148, v150, 5, s91
	ds_write_b64 v148, v[146:147]
.LBB0_1228:
	s_or_b64 exec, exec, s[0:1]
	v_add_u32_e32 v154, 0x80, v197
	s_waitcnt lgkmcnt(1)
	v_add_u32_e32 v148, s4, v154
	s_waitcnt lgkmcnt(0)
	v_ashrrev_i32_e32 v149, 31, v148
	v_lshlrev_b64 v[146:147], 13, v[148:149]
	v_lshl_add_u64 v[146:147], s[68:69], 0, v[146:147]
	v_lshl_add_u64 v[146:147], v[130:131], 2, v[146:147]
	s_waitcnt vmcnt(11)
	v_pk_fma_f32 v[62:63], v[220:221], s[90:91], v[62:63] op_sel_hi:[1,0,1]
	v_pk_fma_f32 v[60:61], v[218:219], s[90:91], v[60:61] op_sel_hi:[1,0,1]
	v_add_f32_e32 v156, v60, v61
	v_add_f32_e32 v158, v62, v63
	v_mul_f32_e32 v161, v60, v60
	v_mul_f32_e32 v163, v61, v61
	v_mul_f32_e32 v165, v62, v62
	v_mul_f32_e32 v167, v63, v63
	s_waitcnt vmcnt(10)
	v_pk_fma_f32 v[58:59], v[224:225], s[90:91], v[58:59] op_sel_hi:[1,0,1]
	v_pk_fma_f32 v[56:57], v[222:223], s[90:91], v[56:57] op_sel_hi:[1,0,1]
	v_mul_f32_e32 v150, v58, v58
	v_pk_fma_f32 v[168:169], v[58:59], v[58:59], v[150:151] op_sel_hi:[1,1,0]
	v_mul_f32_e32 v157, v56, v56
	v_mul_f32_e32 v159, v57, v57
	v_mov_b32_e32 v160, v56
	v_mov_b32_e32 v162, v57
	v_mov_b32_e32 v164, v58
	v_mov_b32_e32 v166, v59
	v_pk_add_f32 v[160:161], v[160:161], v[162:163]
	v_pk_add_f32 v[162:163], v[164:165], v[166:167]
	v_pk_add_f32 v[156:157], v[156:157], v[158:159]
	v_mov_b32_e32 v168, v129
	v_pk_add_f32 v[160:161], v[160:161], v[162:163]
	v_pk_add_f32 v[156:157], v[156:157], v[168:169]
	s_waitcnt vmcnt(9)
	v_pk_fma_f32 v[54:55], v[228:229], s[90:91], v[54:55] op_sel_hi:[1,0,1]
	v_pk_fma_f32 v[52:53], v[226:227], s[90:91], v[52:53] op_sel_hi:[1,0,1]
	v_mul_f32_e32 v171, v52, v52
	v_mul_f32_e32 v173, v53, v53
	v_mul_f32_e32 v175, v54, v54
	v_mul_f32_e32 v177, v55, v55
	v_mov_b32_e32 v170, v52
	v_mov_b32_e32 v172, v53
	v_mov_b32_e32 v174, v54
	v_mov_b32_e32 v176, v55
	v_pk_add_f32 v[156:157], v[160:161], v[156:157]
	v_pk_add_f32 v[158:159], v[170:171], v[172:173]
	v_pk_add_f32 v[160:161], v[174:175], v[176:177]
	s_waitcnt vmcnt(8)
	v_pk_fma_f32 v[50:51], v[232:233], s[90:91], v[50:51] op_sel_hi:[1,0,1]
	v_pk_fma_f32 v[48:49], v[230:231], s[90:91], v[48:49] op_sel_hi:[1,0,1]
	s_mov_b32 s98, 0x160000
	s_mov_b32 s99, 0
	v_lshl_add_u64 v[254:255], v[252:253], 0, s[98:99]
	global_load_dwordx4 v[218:221], v[254:255], off
	global_load_dwordx4 v[222:225], v[254:255], off offset:64
	global_load_dwordx4 v[226:229], v[254:255], off offset:512
	global_load_dwordx4 v[230:233], v[254:255], off offset:576
	v_mul_f32_e32 v179, v50, v50
	v_mul_f32_e32 v151, v48, v48
	v_mul_f32_e32 v153, v49, v49
	v_mul_f32_e32 v181, v51, v51
	v_mov_b32_e32 v150, v48
	v_mov_b32_e32 v152, v49
	v_mov_b32_e32 v178, v50
	v_mov_b32_e32 v180, v51
	v_pk_add_f32 v[158:159], v[158:159], v[160:161]
	v_pk_add_f32 v[150:151], v[150:151], v[152:153]
	v_pk_add_f32 v[152:153], v[178:179], v[180:181]
	v_pk_add_f32 v[156:157], v[156:157], v[158:159]
	v_pk_add_f32 v[150:151], v[150:151], v[152:153]
	s_nop 0
	v_pk_add_f32 v[150:151], v[156:157], v[150:151]
	ds_bpermute_b32 v152, v200, v150
	ds_bpermute_b32 v153, v200, v151
	s_waitcnt lgkmcnt(0)
	v_pk_add_f32 v[150:151], v[150:151], v[152:153]
	ds_bpermute_b32 v152, v199, v150
	ds_bpermute_b32 v153, v199, v151
	s_and_saveexec_b64 s[0:1], vcc
	s_cbranch_execz .LBB0_1230
	s_waitcnt lgkmcnt(0)
	v_pk_add_f32 v[150:151], v[150:151], v[152:153]
	v_lshl_add_u32 v152, v154, 5, s91
	ds_write_b64 v152, v[150:151]
.LBB0_1230:
	s_or_b64 exec, exec, s[0:1]
	s_waitcnt lgkmcnt(1)
	v_add_u32_e32 v152, 0x90, v128
	s_waitcnt lgkmcnt(0)
	v_ashrrev_i32_e32 v153, 31, v152
	v_lshlrev_b64 v[150:151], 13, v[152:153]
	v_lshl_add_u64 v[150:151], s[68:69], 0, v[150:151]
	v_lshl_add_u64 v[150:151], v[130:131], 2, v[150:151]
	s_waitcnt vmcnt(11)
	v_pk_fma_f32 v[46:47], v[236:237], s[90:91], v[46:47] op_sel_hi:[1,0,1]
	v_pk_fma_f32 v[44:45], v[234:235], s[90:91], v[44:45] op_sel_hi:[1,0,1]
	v_add_f32_e32 v158, v44, v45
	v_add_f32_e32 v160, v46, v47
	v_mul_f32_e32 v163, v44, v44
	v_mul_f32_e32 v165, v45, v45
	v_mul_f32_e32 v167, v46, v46
	v_mul_f32_e32 v169, v47, v47
	s_waitcnt vmcnt(10)
	v_pk_fma_f32 v[42:43], v[240:241], s[90:91], v[42:43] op_sel_hi:[1,0,1]
	v_pk_fma_f32 v[40:41], v[238:239], s[90:91], v[40:41] op_sel_hi:[1,0,1]
	v_mul_f32_e32 v154, v42, v42
	v_pk_fma_f32 v[170:171], v[42:43], v[42:43], v[154:155] op_sel_hi:[1,1,0]
	v_mul_f32_e32 v159, v40, v40
	v_mul_f32_e32 v161, v41, v41
	v_mov_b32_e32 v162, v40
	v_mov_b32_e32 v164, v41
	v_mov_b32_e32 v166, v42
	v_mov_b32_e32 v168, v43
	v_pk_add_f32 v[162:163], v[162:163], v[164:165]
	v_pk_add_f32 v[164:165], v[166:167], v[168:169]
	v_pk_add_f32 v[158:159], v[158:159], v[160:161]
	v_mov_b32_e32 v170, v129
	v_pk_add_f32 v[162:163], v[162:163], v[164:165]
	v_pk_add_f32 v[158:159], v[158:159], v[170:171]
	s_waitcnt vmcnt(9)
	v_pk_fma_f32 v[38:39], v[244:245], s[90:91], v[38:39] op_sel_hi:[1,0,1]
	v_pk_fma_f32 v[36:37], v[242:243], s[90:91], v[36:37] op_sel_hi:[1,0,1]
	v_mul_f32_e32 v173, v36, v36
	v_mul_f32_e32 v175, v37, v37
	v_mul_f32_e32 v177, v38, v38
	v_mul_f32_e32 v179, v39, v39
	v_mov_b32_e32 v172, v36
	v_mov_b32_e32 v174, v37
	v_mov_b32_e32 v176, v38
	v_mov_b32_e32 v178, v39
	v_pk_add_f32 v[158:159], v[162:163], v[158:159]
	v_pk_add_f32 v[160:161], v[172:173], v[174:175]
	v_pk_add_f32 v[162:163], v[176:177], v[178:179]
	s_waitcnt vmcnt(8)
	v_pk_fma_f32 v[34:35], v[248:249], s[90:91], v[34:35] op_sel_hi:[1,0,1]
	v_pk_fma_f32 v[32:33], v[246:247], s[90:91], v[32:33] op_sel_hi:[1,0,1]
	v_mul_f32_e32 v181, v34, v34
	v_mul_f32_e32 v155, v32, v32
	v_mul_f32_e32 v157, v33, v33
	v_mul_f32_e32 v183, v35, v35
	v_mov_b32_e32 v154, v32
	v_mov_b32_e32 v156, v33
	v_mov_b32_e32 v180, v34
	v_mov_b32_e32 v182, v35
	v_pk_add_f32 v[160:161], v[160:161], v[162:163]
	v_pk_add_f32 v[154:155], v[154:155], v[156:157]
	v_pk_add_f32 v[156:157], v[180:181], v[182:183]
	v_pk_add_f32 v[158:159], v[158:159], v[160:161]
	v_pk_add_f32 v[154:155], v[154:155], v[156:157]
	s_nop 0
	v_pk_add_f32 v[154:155], v[158:159], v[154:155]
	ds_bpermute_b32 v156, v200, v154
	ds_bpermute_b32 v157, v200, v155
	s_waitcnt lgkmcnt(0)
	v_pk_add_f32 v[154:155], v[154:155], v[156:157]
	ds_bpermute_b32 v156, v199, v154
	ds_bpermute_b32 v157, v199, v155
	s_and_saveexec_b64 s[0:1], vcc
	s_cbranch_execz .LBB0_1232
	s_waitcnt lgkmcnt(0)
	v_pk_add_f32 v[154:155], v[154:155], v[156:157]
	ds_write_b64 v201, v[154:155] offset:4608
.LBB0_1232:
	s_or_b64 exec, exec, s[0:1]
	s_waitcnt lgkmcnt(1)
	v_add_u32_e32 v156, 0xa0, v128
	s_waitcnt lgkmcnt(0)
	v_ashrrev_i32_e32 v157, 31, v156
	v_lshlrev_b64 v[154:155], 13, v[156:157]
	v_lshl_add_u64 v[154:155], s[68:69], 0, v[154:155]
	v_lshl_add_u64 v[154:155], v[130:131], 2, v[154:155]
	s_waitcnt vmcnt(7)
	v_pk_fma_f32 v[160:161], v[204:205], s[90:91], v[30:31] op_sel_hi:[1,0,1]
	v_pk_fma_f32 v[158:159], v[202:203], s[90:91], v[28:29] op_sel_hi:[1,0,1]
	v_add_f32_e32 v174, v158, v159
	v_add_f32_e32 v176, v160, v161
	v_mul_f32_e32 v179, v158, v158
	v_mul_f32_e32 v181, v159, v159
	v_mul_f32_e32 v183, v160, v160
	v_mul_f32_e32 v185, v161, v161
	s_waitcnt vmcnt(6)
	v_pk_fma_f32 v[164:165], v[208:209], s[90:91], v[26:27] op_sel_hi:[1,0,1]
	v_pk_fma_f32 v[162:163], v[206:207], s[90:91], v[24:25] op_sel_hi:[1,0,1]
	v_mul_f32_e32 v24, v164, v164
	v_pk_fma_f32 v[28:29], v[164:165], v[164:165], v[24:25] op_sel_hi:[1,1,0]
	v_mul_f32_e32 v175, v162, v162
	v_mul_f32_e32 v177, v163, v163
	v_mov_b32_e32 v178, v162
	v_mov_b32_e32 v180, v163
	v_mov_b32_e32 v182, v164
	v_mov_b32_e32 v184, v165
	v_pk_add_f32 v[178:179], v[178:179], v[180:181]
	v_pk_add_f32 v[180:181], v[182:183], v[184:185]
	v_pk_add_f32 v[174:175], v[174:175], v[176:177]
	v_mov_b32_e32 v28, v129
	v_pk_add_f32 v[178:179], v[178:179], v[180:181]
	v_pk_add_f32 v[28:29], v[174:175], v[28:29]
	s_waitcnt vmcnt(5)
	v_pk_fma_f32 v[168:169], v[212:213], s[90:91], v[22:23] op_sel_hi:[1,0,1]
	v_pk_fma_f32 v[166:167], v[210:211], s[90:91], v[20:21] op_sel_hi:[1,0,1]
	v_mul_f32_e32 v25, v166, v166
	v_mul_f32_e32 v27, v167, v167
	v_mul_f32_e32 v31, v168, v168
	v_mul_f32_e32 v187, v169, v169
	v_mov_b32_e32 v24, v166
	v_mov_b32_e32 v26, v167
	v_mov_b32_e32 v30, v168
	v_mov_b32_e32 v186, v169
	v_pk_add_f32 v[24:25], v[24:25], v[26:27]
	v_pk_add_f32 v[26:27], v[30:31], v[186:187]
	v_pk_add_f32 v[28:29], v[178:179], v[28:29]
	v_pk_add_f32 v[24:25], v[24:25], v[26:27]
	s_waitcnt vmcnt(4)
	v_pk_fma_f32 v[172:173], v[216:217], s[90:91], v[18:19] op_sel_hi:[1,0,1]
	v_pk_fma_f32 v[170:171], v[214:215], s[90:91], v[16:17] op_sel_hi:[1,0,1]
	v_mul_f32_e32 v21, v172, v172
	v_mul_f32_e32 v17, v170, v170
	v_mul_f32_e32 v19, v171, v171
	v_mul_f32_e32 v23, v173, v173
	v_mov_b32_e32 v16, v170
	v_mov_b32_e32 v18, v171
	v_mov_b32_e32 v20, v172
	v_mov_b32_e32 v22, v173
	v_pk_add_f32 v[16:17], v[16:17], v[18:19]
	v_pk_add_f32 v[18:19], v[20:21], v[22:23]
	v_pk_add_f32 v[24:25], v[28:29], v[24:25]
	v_pk_add_f32 v[16:17], v[16:17], v[18:19]
	s_nop 0
	v_pk_add_f32 v[16:17], v[24:25], v[16:17]
	ds_bpermute_b32 v18, v200, v16
	ds_bpermute_b32 v19, v200, v17
	s_waitcnt lgkmcnt(0)
	v_pk_add_f32 v[16:17], v[16:17], v[18:19]
	ds_bpermute_b32 v18, v199, v16
	ds_bpermute_b32 v19, v199, v17
	s_and_saveexec_b64 s[0:1], vcc
	s_cbranch_execz .LBB0_1234
	s_waitcnt lgkmcnt(0)
	v_pk_add_f32 v[16:17], v[16:17], v[18:19]
	ds_write_b64 v201, v[16:17] offset:5120
.LBB0_1234:
	s_or_b64 exec, exec, s[0:1]
	v_add_u32_e32 v176, 0xb0, v128
	v_ashrrev_i32_e32 v177, 31, v176
	v_lshlrev_b64 v[16:17], 13, v[176:177]
	v_lshl_add_u64 v[16:17], s[68:69], 0, v[16:17]
	v_lshl_add_u64 v[174:175], v[130:131], 2, v[16:17]
	s_waitcnt lgkmcnt(0)
	s_waitcnt vmcnt(3)
	v_pk_fma_f32 v[180:181], v[220:221], s[90:91], v[14:15] op_sel_hi:[1,0,1]
	v_pk_fma_f32 v[178:179], v[218:219], s[90:91], v[12:13] op_sel_hi:[1,0,1]
	v_add_f32_e32 v16, v178, v179
	v_add_f32_e32 v18, v180, v181
	v_mul_f32_e32 v21, v178, v178
	v_mul_f32_e32 v23, v179, v179
	v_mul_f32_e32 v25, v180, v180
	v_mul_f32_e32 v27, v181, v181
	s_waitcnt vmcnt(2)
	v_pk_fma_f32 v[184:185], v[224:225], s[90:91], v[10:11] op_sel_hi:[1,0,1]
	v_pk_fma_f32 v[182:183], v[222:223], s[90:91], v[8:9] op_sel_hi:[1,0,1]
	v_mul_f32_e32 v8, v184, v184
	v_pk_fma_f32 v[12:13], v[184:185], v[184:185], v[8:9] op_sel_hi:[1,1,0]
	v_mul_f32_e32 v17, v182, v182
	v_mul_f32_e32 v19, v183, v183
	v_mov_b32_e32 v20, v182
	v_mov_b32_e32 v22, v183
	v_mov_b32_e32 v24, v184
	v_mov_b32_e32 v26, v185
	v_pk_add_f32 v[20:21], v[20:21], v[22:23]
	v_pk_add_f32 v[22:23], v[24:25], v[26:27]
	v_pk_add_f32 v[16:17], v[16:17], v[18:19]
	v_mov_b32_e32 v12, v129
	v_pk_add_f32 v[20:21], v[20:21], v[22:23]
	v_pk_add_f32 v[12:13], v[16:17], v[12:13]
	s_waitcnt vmcnt(1)
	v_pk_fma_f32 v[188:189], v[228:229], s[90:91], v[6:7] op_sel_hi:[1,0,1]
	v_pk_fma_f32 v[186:187], v[226:227], s[90:91], v[4:5] op_sel_hi:[1,0,1]
	v_mul_f32_e32 v9, v186, v186
	v_mul_f32_e32 v11, v187, v187
	v_mul_f32_e32 v15, v188, v188
	v_mul_f32_e32 v29, v189, v189
	v_mov_b32_e32 v8, v186
	v_mov_b32_e32 v10, v187
	v_mov_b32_e32 v14, v188
	v_mov_b32_e32 v28, v189
	v_pk_add_f32 v[8:9], v[8:9], v[10:11]
	v_pk_add_f32 v[10:11], v[14:15], v[28:29]
	v_pk_add_f32 v[12:13], v[20:21], v[12:13]
	v_pk_add_f32 v[8:9], v[8:9], v[10:11]
	s_waitcnt vmcnt(0)
	v_pk_fma_f32 v[192:193], v[232:233], s[90:91], v[2:3] op_sel_hi:[1,0,1]
	v_pk_fma_f32 v[190:191], v[230:231], s[90:91], v[0:1] op_sel_hi:[1,0,1]
	v_mul_f32_e32 v5, v192, v192
	v_mul_f32_e32 v1, v190, v190
	v_mul_f32_e32 v3, v191, v191
	v_mul_f32_e32 v7, v193, v193
	v_mov_b32_e32 v0, v190
	v_mov_b32_e32 v2, v191
	v_mov_b32_e32 v4, v192
	v_mov_b32_e32 v6, v193
	v_pk_add_f32 v[0:1], v[0:1], v[2:3]
	v_pk_add_f32 v[2:3], v[4:5], v[6:7]
	v_pk_add_f32 v[8:9], v[12:13], v[8:9]
	v_pk_add_f32 v[0:1], v[0:1], v[2:3]
	s_nop 0
	v_pk_add_f32 v[0:1], v[8:9], v[0:1]
	ds_bpermute_b32 v2, v200, v0
	ds_bpermute_b32 v3, v200, v1
	s_waitcnt lgkmcnt(0)
	v_pk_add_f32 v[0:1], v[0:1], v[2:3]
	ds_bpermute_b32 v2, v199, v0
	ds_bpermute_b32 v3, v199, v1
	s_and_saveexec_b64 s[0:1], vcc
	s_cbranch_execz .LBB0_1236
	s_waitcnt lgkmcnt(0)
	v_pk_add_f32 v[0:1], v[0:1], v[2:3]
	ds_write_b64 v201, v[0:1] offset:5632

.LBB0_1733:
	v_ashrrev_i32_e32 v128, 2, v198
	v_and_b32_e32 v128, -4, v128
	v_and_b32_e32 v132, 64, v194
	v_add_u32_e32 v130, s75, v128
	v_xor_b32_e32 v128, 16, v194
	v_add_u32_e32 v132, 64, v132
	v_cmp_lt_i32_e32 vcc, v128, v132
	s_lshl_b32 s6, s8, 8
	v_ashrrev_i32_e32 v131, 31, v130
	v_cndmask_b32_e32 v128, v194, v128, vcc
	v_lshlrev_b32_e32 v200, 2, v128
	v_xor_b32_e32 v128, 32, v194
	v_cmp_lt_i32_e32 vcc, v128, v132
	s_barrier
	v_lshl_add_u32 v201, v197, 5, s97
	v_cndmask_b32_e32 v128, v194, v128, vcc
	v_lshlrev_b32_e32 v199, 2, v128
	v_add_u32_e32 v128, s6, v197
	v_lshlrev_b64 v[132:133], 13, v[128:129]
	v_lshl_add_u64 v[132:133], s[68:69], 0, v[132:133]
	v_lshl_add_u64 v[132:133], v[130:131], 2, v[132:133]
	v_mov_b64_e32 v[252:253], v[132:133]
	global_load_dwordx4 v[202:205], v[252:253], off
	global_load_dwordx4 v[206:209], v[252:253], off offset:64
	global_load_dwordx4 v[210:213], v[252:253], off offset:512
	global_load_dwordx4 v[214:217], v[252:253], off offset:576
	s_mov_b32 s98, 0x20000
	s_mov_b32 s99, 0
	v_lshl_add_u64 v[254:255], v[252:253], 0, s[98:99]
	global_load_dwordx4 v[218:221], v[254:255], off
	global_load_dwordx4 v[222:225], v[254:255], off offset:64
	global_load_dwordx4 v[226:229], v[254:255], off offset:512
	global_load_dwordx4 v[230:233], v[254:255], off offset:576
	s_mov_b32 s98, 0x40000
	s_mov_b32 s99, 0
	v_lshl_add_u64 v[254:255], v[252:253], 0, s[98:99]
	global_load_dwordx4 v[234:237], v[254:255], off
	global_load_dwordx4 v[238:241], v[254:255], off offset:64
	global_load_dwordx4 v[242:245], v[254:255], off offset:512
	global_load_dwordx4 v[246:249], v[254:255], off offset:576
	v_cmp_gt_u32_e32 vcc, 16, v198
	s_waitcnt vmcnt(11)
	v_pk_fma_f32 v[126:127], v[204:205], s[96:97], v[126:127] op_sel_hi:[1,0,1]
	v_pk_fma_f32 v[124:125], v[202:203], s[96:97], v[124:125] op_sel_hi:[1,0,1]
	v_add_f32_e32 v138, v124, v125
	v_add_f32_e32 v140, v126, v127
	v_mul_f32_e32 v143, v124, v124
	v_mul_f32_e32 v145, v125, v125
	v_mul_f32_e32 v147, v126, v126
	v_mul_f32_e32 v149, v127, v127
	s_waitcnt vmcnt(10)
	v_pk_fma_f32 v[122:123], v[208:209], s[96:97], v[122:123] op_sel_hi:[1,0,1]
	v_pk_fma_f32 v[120:121], v[206:207], s[96:97], v[120:121] op_sel_hi:[1,0,1]
	v_mul_f32_e32 v134, v122, v122
	v_pk_fma_f32 v[150:151], v[122:123], v[122:123], v[134:135] op_sel_hi:[1,1,0]
	v_mul_f32_e32 v139, v120, v120
	v_mul_f32_e32 v141, v121, v121
	v_mov_b32_e32 v142, v120
	v_mov_b32_e32 v144, v121
	v_mov_b32_e32 v146, v122
	v_mov_b32_e32 v148, v123
	v_pk_add_f32 v[142:143], v[142:143], v[144:145]
	v_pk_add_f32 v[144:145], v[146:147], v[148:149]
	v_pk_add_f32 v[138:139], v[138:139], v[140:141]
	v_mov_b32_e32 v150, v129
	v_pk_add_f32 v[142:143], v[142:143], v[144:145]
	v_pk_add_f32 v[138:139], v[138:139], v[150:151]
	s_waitcnt vmcnt(9)
	v_pk_fma_f32 v[118:119], v[212:213], s[96:97], v[118:119] op_sel_hi:[1,0,1]
	v_pk_fma_f32 v[116:117], v[210:211], s[96:97], v[116:117] op_sel_hi:[1,0,1]
	v_mul_f32_e32 v153, v116, v116
	v_mul_f32_e32 v155, v117, v117
	v_mul_f32_e32 v157, v118, v118
	v_mul_f32_e32 v159, v119, v119
	v_mov_b32_e32 v152, v116
	v_mov_b32_e32 v154, v117
	v_mov_b32_e32 v156, v118
	v_mov_b32_e32 v158, v119
	v_pk_add_f32 v[138:139], v[142:143], v[138:139]
	v_pk_add_f32 v[140:141], v[152:153], v[154:155]
	v_pk_add_f32 v[142:143], v[156:157], v[158:159]
	s_waitcnt vmcnt(8)
	v_pk_fma_f32 v[114:115], v[216:217], s[96:97], v[114:115] op_sel_hi:[1,0,1]
	v_pk_fma_f32 v[112:113], v[214:215], s[96:97], v[112:113] op_sel_hi:[1,0,1]
	s_mov_b32 s98, 0x60000
	s_mov_b32 s99, 0
	v_lshl_add_u64 v[254:255], v[252:253], 0, s[98:99]
	global_load_dwordx4 v[202:205], v[254:255], off
	global_load_dwordx4 v[206:209], v[254:255], off offset:64
	global_load_dwordx4 v[210:213], v[254:255], off offset:512
	global_load_dwordx4 v[214:217], v[254:255], off offset:576
	v_mul_f32_e32 v161, v114, v114
	v_mul_f32_e32 v135, v112, v112
	v_mul_f32_e32 v137, v113, v113
	v_mul_f32_e32 v163, v115, v115
	v_mov_b32_e32 v134, v112
	v_mov_b32_e32 v136, v113
	v_mov_b32_e32 v160, v114
	v_mov_b32_e32 v162, v115
	v_pk_add_f32 v[140:141], v[140:141], v[142:143]
	v_pk_add_f32 v[134:135], v[134:135], v[136:137]
	v_pk_add_f32 v[136:137], v[160:161], v[162:163]
	v_pk_add_f32 v[138:139], v[138:139], v[140:141]
	v_pk_add_f32 v[134:135], v[134:135], v[136:137]
	s_nop 0
	v_pk_add_f32 v[134:135], v[138:139], v[134:135]
	ds_bpermute_b32 v136, v200, v134
	ds_bpermute_b32 v137, v200, v135
	s_waitcnt lgkmcnt(0)
	v_pk_add_f32 v[134:135], v[134:135], v[136:137]
	ds_bpermute_b32 v136, v199, v134
	ds_bpermute_b32 v137, v199, v135
	s_and_saveexec_b64 s[4:5], vcc
	s_cbranch_execz .LBB0_1735
	s_waitcnt lgkmcnt(0)
	v_pk_add_f32 v[134:135], v[134:135], v[136:137]
	ds_write_b64 v201, v[134:135]
.LBB0_1735:
	s_or_b64 exec, exec, s[4:5]
	v_or_b32_e32 v142, 16, v197
	s_waitcnt lgkmcnt(1)
	v_add_u32_e32 v136, s6, v142
	s_waitcnt lgkmcnt(0)
	v_mov_b32_e32 v137, v129
	v_lshlrev_b64 v[134:135], 13, v[136:137]
	v_lshl_add_u64 v[134:135], s[68:69], 0, v[134:135]
	v_lshl_add_u64 v[134:135], v[130:131], 2, v[134:135]
	s_waitcnt vmcnt(11)
	v_pk_fma_f32 v[110:111], v[220:221], s[96:97], v[110:111] op_sel_hi:[1,0,1]
	v_pk_fma_f32 v[108:109], v[218:219], s[96:97], v[108:109] op_sel_hi:[1,0,1]
	v_add_f32_e32 v144, v108, v109
	v_add_f32_e32 v146, v110, v111
	v_mul_f32_e32 v149, v108, v108
	v_mul_f32_e32 v151, v109, v109
	v_mul_f32_e32 v153, v110, v110
	v_mul_f32_e32 v155, v111, v111
	s_waitcnt vmcnt(10)
	v_pk_fma_f32 v[106:107], v[224:225], s[96:97], v[106:107] op_sel_hi:[1,0,1]
	v_pk_fma_f32 v[104:105], v[222:223], s[96:97], v[104:105] op_sel_hi:[1,0,1]
	v_mul_f32_e32 v138, v106, v106
	v_pk_fma_f32 v[156:157], v[106:107], v[106:107], v[138:139] op_sel_hi:[1,1,0]
	v_mul_f32_e32 v145, v104, v104
	v_mul_f32_e32 v147, v105, v105
	v_mov_b32_e32 v148, v104
	v_mov_b32_e32 v150, v105
	v_mov_b32_e32 v152, v106
	v_mov_b32_e32 v154, v107
	v_pk_add_f32 v[148:149], v[148:149], v[150:151]
	v_pk_add_f32 v[150:151], v[152:153], v[154:155]
	v_pk_add_f32 v[144:145], v[144:145], v[146:147]
	v_mov_b32_e32 v156, v129
	v_pk_add_f32 v[148:149], v[148:149], v[150:151]
	v_pk_add_f32 v[144:145], v[144:145], v[156:157]
	s_waitcnt vmcnt(9)
	v_pk_fma_f32 v[102:103], v[228:229], s[96:97], v[102:103] op_sel_hi:[1,0,1]
	v_pk_fma_f32 v[100:101], v[226:227], s[96:97], v[100:101] op_sel_hi:[1,0,1]
	v_mul_f32_e32 v159, v100, v100
	v_mul_f32_e32 v161, v101, v101
	v_mul_f32_e32 v163, v102, v102
	v_mul_f32_e32 v165, v103, v103
	v_mov_b32_e32 v158, v100
	v_mov_b32_e32 v160, v101
	v_mov_b32_e32 v162, v102
	v_mov_b32_e32 v164, v103
	v_pk_add_f32 v[144:145], v[148:149], v[144:145]
	v_pk_add_f32 v[146:147], v[158:159], v[160:161]
	v_pk_add_f32 v[148:149], v[162:163], v[164:165]
	s_waitcnt vmcnt(8)
	v_pk_fma_f32 v[98:99], v[232:233], s[96:97], v[98:99] op_sel_hi:[1,0,1]
	v_pk_fma_f32 v[96:97], v[230:231], s[96:97], v[96:97] op_sel_hi:[1,0,1]
	s_mov_b32 s98, 0x100000
	s_mov_b32 s99, 0
	v_lshl_add_u64 v[254:255], v[252:253], 0, s[98:99]
	global_load_dwordx4 v[218:221], v[254:255], off
	global_load_dwordx4 v[222:225], v[254:255], off offset:64
	global_load_dwordx4 v[226:229], v[254:255], off offset:512
	global_load_dwordx4 v[230:233], v[254:255], off offset:576
	v_mul_f32_e32 v167, v98, v98
	v_mul_f32_e32 v139, v96, v96
	v_mul_f32_e32 v141, v97, v97
	v_mul_f32_e32 v169, v99, v99
	v_mov_b32_e32 v138, v96
	v_mov_b32_e32 v140, v97
	v_mov_b32_e32 v166, v98
	v_mov_b32_e32 v168, v99
	v_pk_add_f32 v[146:147], v[146:147], v[148:149]
	v_pk_add_f32 v[138:139], v[138:139], v[140:141]
	v_pk_add_f32 v[140:141], v[166:167], v[168:169]
	v_pk_add_f32 v[144:145], v[144:145], v[146:147]
	v_pk_add_f32 v[138:139], v[138:139], v[140:141]
	s_nop 0
	v_pk_add_f32 v[138:139], v[144:145], v[138:139]
	ds_bpermute_b32 v140, v200, v138
	ds_bpermute_b32 v141, v200, v139
	s_waitcnt lgkmcnt(0)
	v_pk_add_f32 v[138:139], v[138:139], v[140:141]
	ds_bpermute_b32 v140, v199, v138
	ds_bpermute_b32 v141, v199, v139
	s_and_saveexec_b64 s[4:5], vcc
	s_cbranch_execz .LBB0_1737
	s_waitcnt lgkmcnt(0)
	v_pk_add_f32 v[138:139], v[138:139], v[140:141]
	v_lshl_add_u32 v140, v142, 5, s97
	ds_write_b64 v140, v[138:139]
.LBB0_1737:
	s_or_b64 exec, exec, s[4:5]
	v_or_b32_e32 v146, 32, v197
	s_waitcnt lgkmcnt(1)
	v_add_u32_e32 v140, s6, v146
	s_waitcnt lgkmcnt(0)
	v_mov_b32_e32 v141, v129
	v_lshlrev_b64 v[138:139], 13, v[140:141]
	v_lshl_add_u64 v[138:139], s[68:69], 0, v[138:139]
	v_lshl_add_u64 v[138:139], v[130:131], 2, v[138:139]
	s_waitcnt vmcnt(11)
	v_pk_fma_f32 v[94:95], v[236:237], s[96:97], v[94:95] op_sel_hi:[1,0,1]
	v_pk_fma_f32 v[92:93], v[234:235], s[96:97], v[92:93] op_sel_hi:[1,0,1]
	v_add_f32_e32 v148, v92, v93
	v_add_f32_e32 v150, v94, v95
	v_mul_f32_e32 v153, v92, v92
	v_mul_f32_e32 v155, v93, v93
	v_mul_f32_e32 v157, v94, v94
	v_mul_f32_e32 v159, v95, v95
	s_waitcnt vmcnt(10)
	v_pk_fma_f32 v[90:91], v[240:241], s[96:97], v[90:91] op_sel_hi:[1,0,1]
	v_pk_fma_f32 v[88:89], v[238:239], s[96:97], v[88:89] op_sel_hi:[1,0,1]
	v_mul_f32_e32 v142, v90, v90
	v_pk_fma_f32 v[160:161], v[90:91], v[90:91], v[142:143] op_sel_hi:[1,1,0]
	v_mul_f32_e32 v149, v88, v88
	v_mul_f32_e32 v151, v89, v89
	v_mov_b32_e32 v152, v88
	v_mov_b32_e32 v154, v89
	v_mov_b32_e32 v156, v90
	v_mov_b32_e32 v158, v91
	v_pk_add_f32 v[152:153], v[152:153], v[154:155]
	v_pk_add_f32 v[154:155], v[156:157], v[158:159]
	v_pk_add_f32 v[148:149], v[148:149], v[150:151]
	v_mov_b32_e32 v160, v129
	v_pk_add_f32 v[152:153], v[152:153], v[154:155]
	v_pk_add_f32 v[148:149], v[148:149], v[160:161]
	s_waitcnt vmcnt(9)
	v_pk_fma_f32 v[86:87], v[244:245], s[96:97], v[86:87] op_sel_hi:[1,0,1]
	v_pk_fma_f32 v[84:85], v[242:243], s[96:97], v[84:85] op_sel_hi:[1,0,1]
	v_mul_f32_e32 v163, v84, v84
	v_mul_f32_e32 v165, v85, v85
	v_mul_f32_e32 v167, v86, v86
	v_mul_f32_e32 v169, v87, v87
	v_mov_b32_e32 v162, v84
	v_mov_b32_e32 v164, v85
	v_mov_b32_e32 v166, v86
	v_mov_b32_e32 v168, v87
	v_pk_add_f32 v[148:149], v[152:153], v[148:149]
	v_pk_add_f32 v[150:151], v[162:163], v[164:165]
	v_pk_add_f32 v[152:153], v[166:167], v[168:169]
	s_waitcnt vmcnt(8)
	v_pk_fma_f32 v[82:83], v[248:249], s[96:97], v[82:83] op_sel_hi:[1,0,1]
	v_pk_fma_f32 v[80:81], v[246:247], s[96:97], v[80:81] op_sel_hi:[1,0,1]
	s_mov_b32 s98, 0x120000
	s_mov_b32 s99, 0
	v_lshl_add_u64 v[254:255], v[252:253], 0, s[98:99]
	global_load_dwordx4 v[234:237], v[254:255], off
	global_load_dwordx4 v[238:241], v[254:255], off offset:64
	global_load_dwordx4 v[242:245], v[254:255], off offset:512
	global_load_dwordx4 v[246:249], v[254:255], off offset:576
	v_mul_f32_e32 v171, v82, v82
	v_mul_f32_e32 v143, v80, v80
	v_mul_f32_e32 v145, v81, v81
	v_mul_f32_e32 v173, v83, v83
	v_mov_b32_e32 v142, v80
	v_mov_b32_e32 v144, v81
	v_mov_b32_e32 v170, v82
	v_mov_b32_e32 v172, v83
	v_pk_add_f32 v[150:151], v[150:151], v[152:153]
	v_pk_add_f32 v[142:143], v[142:143], v[144:145]
	v_pk_add_f32 v[144:145], v[170:171], v[172:173]
	v_pk_add_f32 v[148:149], v[148:149], v[150:151]
	v_pk_add_f32 v[142:143], v[142:143], v[144:145]
	s_nop 0
	v_pk_add_f32 v[142:143], v[148:149], v[142:143]
	ds_bpermute_b32 v144, v200, v142
	ds_bpermute_b32 v145, v200, v143
	s_waitcnt lgkmcnt(0)
	v_pk_add_f32 v[142:143], v[142:143], v[144:145]
	ds_bpermute_b32 v144, v199, v142
	ds_bpermute_b32 v145, v199, v143
	s_and_saveexec_b64 s[4:5], vcc
	s_cbranch_execz .LBB0_1739
	s_waitcnt lgkmcnt(0)
	v_pk_add_f32 v[142:143], v[142:143], v[144:145]
	v_lshl_add_u32 v144, v146, 5, s97
	ds_write_b64 v144, v[142:143]
.LBB0_1739:
	s_or_b64 exec, exec, s[4:5]
	v_or_b32_e32 v150, 48, v197
	s_waitcnt lgkmcnt(1)
	v_add_u32_e32 v144, s6, v150
	s_waitcnt lgkmcnt(0)
	v_mov_b32_e32 v145, v129
	v_lshlrev_b64 v[142:143], 13, v[144:145]
	v_lshl_add_u64 v[142:143], s[68:69], 0, v[142:143]
	v_lshl_add_u64 v[142:143], v[130:131], 2, v[142:143]
	s_waitcnt vmcnt(11)
	v_pk_fma_f32 v[78:79], v[204:205], s[96:97], v[78:79] op_sel_hi:[1,0,1]
	v_pk_fma_f32 v[76:77], v[202:203], s[96:97], v[76:77] op_sel_hi:[1,0,1]
	v_add_f32_e32 v152, v76, v77
	v_add_f32_e32 v154, v78, v79
	v_mul_f32_e32 v157, v76, v76
	v_mul_f32_e32 v159, v77, v77
	v_mul_f32_e32 v161, v78, v78
	v_mul_f32_e32 v163, v79, v79
	s_waitcnt vmcnt(10)
	v_pk_fma_f32 v[74:75], v[208:209], s[96:97], v[74:75] op_sel_hi:[1,0,1]
	v_pk_fma_f32 v[72:73], v[206:207], s[96:97], v[72:73] op_sel_hi:[1,0,1]
	v_mul_f32_e32 v146, v74, v74
	v_pk_fma_f32 v[164:165], v[74:75], v[74:75], v[146:147] op_sel_hi:[1,1,0]
	v_mul_f32_e32 v153, v72, v72
	v_mul_f32_e32 v155, v73, v73
	v_mov_b32_e32 v156, v72
	v_mov_b32_e32 v158, v73
	v_mov_b32_e32 v160, v74
	v_mov_b32_e32 v162, v75
	v_pk_add_f32 v[156:157], v[156:157], v[158:159]
	v_pk_add_f32 v[158:159], v[160:161], v[162:163]
	v_pk_add_f32 v[152:153], v[152:153], v[154:155]
	v_mov_b32_e32 v164, v129
	v_pk_add_f32 v[156:157], v[156:157], v[158:159]
	v_pk_add_f32 v[152:153], v[152:153], v[164:165]
	s_waitcnt vmcnt(9)
	v_pk_fma_f32 v[70:71], v[212:213], s[96:97], v[70:71] op_sel_hi:[1,0,1]
	v_pk_fma_f32 v[68:69], v[210:211], s[96:97], v[68:69] op_sel_hi:[1,0,1]
	v_mul_f32_e32 v167, v68, v68
	v_mul_f32_e32 v169, v69, v69
	v_mul_f32_e32 v171, v70, v70
	v_mul_f32_e32 v173, v71, v71
	v_mov_b32_e32 v166, v68
	v_mov_b32_e32 v168, v69
	v_mov_b32_e32 v170, v70
	v_mov_b32_e32 v172, v71
	v_pk_add_f32 v[152:153], v[156:157], v[152:153]
	v_pk_add_f32 v[154:155], v[166:167], v[168:169]
	v_pk_add_f32 v[156:157], v[170:171], v[172:173]
	s_waitcnt vmcnt(8)
	v_pk_fma_f32 v[66:67], v[216:217], s[96:97], v[66:67] op_sel_hi:[1,0,1]
	v_pk_fma_f32 v[64:65], v[214:215], s[96:97], v[64:65] op_sel_hi:[1,0,1]
	s_mov_b32 s98, 0x140000
	s_mov_b32 s99, 0
	v_lshl_add_u64 v[254:255], v[252:253], 0, s[98:99]
	global_load_dwordx4 v[202:205], v[254:255], off
	global_load_dwordx4 v[206:209], v[254:255], off offset:64
	global_load_dwordx4 v[210:213], v[254:255], off offset:512
	global_load_dwordx4 v[214:217], v[254:255], off offset:576
	v_mul_f32_e32 v175, v66, v66
	v_mul_f32_e32 v147, v64, v64
	v_mul_f32_e32 v149, v65, v65
	v_mul_f32_e32 v177, v67, v67
	v_mov_b32_e32 v146, v64
	v_mov_b32_e32 v148, v65
	v_mov_b32_e32 v174, v66
	v_mov_b32_e32 v176, v67
	v_pk_add_f32 v[154:155], v[154:155], v[156:157]
	v_pk_add_f32 v[146:147], v[146:147], v[148:149]
	v_pk_add_f32 v[148:149], v[174:175], v[176:177]
	v_pk_add_f32 v[152:153], v[152:153], v[154:155]
	v_pk_add_f32 v[146:147], v[146:147], v[148:149]
	s_nop 0
	v_pk_add_f32 v[146:147], v[152:153], v[146:147]
	ds_bpermute_b32 v148, v200, v146
	ds_bpermute_b32 v149, v200, v147
	s_waitcnt lgkmcnt(0)
	v_pk_add_f32 v[146:147], v[146:147], v[148:149]
	ds_bpermute_b32 v148, v199, v146
	ds_bpermute_b32 v149, v199, v147
	s_and_saveexec_b64 s[4:5], vcc
	s_cbranch_execz .LBB0_1741
	s_waitcnt lgkmcnt(0)
	v_pk_add_f32 v[146:147], v[146:147], v[148:149]
	v_lshl_add_u32 v148, v150, 5, s97
	ds_write_b64 v148, v[146:147]
.LBB0_1741:
	s_or_b64 exec, exec, s[4:5]
	v_add_u32_e32 v154, 0x80, v197
	s_waitcnt lgkmcnt(1)
	v_add_u32_e32 v148, s6, v154
	s_waitcnt lgkmcnt(0)
	v_ashrrev_i32_e32 v149, 31, v148
	v_lshlrev_b64 v[146:147], 13, v[148:149]
	v_lshl_add_u64 v[146:147], s[68:69], 0, v[146:147]
	v_lshl_add_u64 v[146:147], v[130:131], 2, v[146:147]
	s_waitcnt vmcnt(11)
	v_pk_fma_f32 v[62:63], v[220:221], s[96:97], v[62:63] op_sel_hi:[1,0,1]
	v_pk_fma_f32 v[60:61], v[218:219], s[96:97], v[60:61] op_sel_hi:[1,0,1]
	v_add_f32_e32 v156, v60, v61
	v_add_f32_e32 v158, v62, v63
	v_mul_f32_e32 v161, v60, v60
	v_mul_f32_e32 v163, v61, v61
	v_mul_f32_e32 v165, v62, v62
	v_mul_f32_e32 v167, v63, v63
	s_waitcnt vmcnt(10)
	v_pk_fma_f32 v[58:59], v[224:225], s[96:97], v[58:59] op_sel_hi:[1,0,1]
	v_pk_fma_f32 v[56:57], v[222:223], s[96:97], v[56:57] op_sel_hi:[1,0,1]
	v_mul_f32_e32 v150, v58, v58
	v_pk_fma_f32 v[168:169], v[58:59], v[58:59], v[150:151] op_sel_hi:[1,1,0]
	v_mul_f32_e32 v157, v56, v56
	v_mul_f32_e32 v159, v57, v57
	v_mov_b32_e32 v160, v56
	v_mov_b32_e32 v162, v57
	v_mov_b32_e32 v164, v58
	v_mov_b32_e32 v166, v59
	v_pk_add_f32 v[160:161], v[160:161], v[162:163]
	v_pk_add_f32 v[162:163], v[164:165], v[166:167]
	v_pk_add_f32 v[156:157], v[156:157], v[158:159]
	v_mov_b32_e32 v168, v129
	v_pk_add_f32 v[160:161], v[160:161], v[162:163]
	v_pk_add_f32 v[156:157], v[156:157], v[168:169]
	s_waitcnt vmcnt(9)
	v_pk_fma_f32 v[54:55], v[228:229], s[96:97], v[54:55] op_sel_hi:[1,0,1]
	v_pk_fma_f32 v[52:53], v[226:227], s[96:97], v[52:53] op_sel_hi:[1,0,1]
	v_mul_f32_e32 v171, v52, v52
	v_mul_f32_e32 v173, v53, v53
	v_mul_f32_e32 v175, v54, v54
	v_mul_f32_e32 v177, v55, v55
	v_mov_b32_e32 v170, v52
	v_mov_b32_e32 v172, v53
	v_mov_b32_e32 v174, v54
	v_mov_b32_e32 v176, v55
	v_pk_add_f32 v[156:157], v[160:161], v[156:157]
	v_pk_add_f32 v[158:159], v[170:171], v[172:173]
	v_pk_add_f32 v[160:161], v[174:175], v[176:177]
	s_waitcnt vmcnt(8)
	v_pk_fma_f32 v[50:51], v[232:233], s[96:97], v[50:51] op_sel_hi:[1,0,1]
	v_pk_fma_f32 v[48:49], v[230:231], s[96:97], v[48:49] op_sel_hi:[1,0,1]
	s_mov_b32 s98, 0x160000
	s_mov_b32 s99, 0
	v_lshl_add_u64 v[254:255], v[252:253], 0, s[98:99]
	global_load_dwordx4 v[218:221], v[254:255], off
	global_load_dwordx4 v[222:225], v[254:255], off offset:64
	global_load_dwordx4 v[226:229], v[254:255], off offset:512
	global_load_dwordx4 v[230:233], v[254:255], off offset:576
	v_mul_f32_e32 v179, v50, v50
	v_mul_f32_e32 v151, v48, v48
	v_mul_f32_e32 v153, v49, v49
	v_mul_f32_e32 v181, v51, v51
	v_mov_b32_e32 v150, v48
	v_mov_b32_e32 v152, v49
	v_mov_b32_e32 v178, v50
	v_mov_b32_e32 v180, v51
	v_pk_add_f32 v[158:159], v[158:159], v[160:161]
	v_pk_add_f32 v[150:151], v[150:151], v[152:153]
	v_pk_add_f32 v[152:153], v[178:179], v[180:181]
	v_pk_add_f32 v[156:157], v[156:157], v[158:159]
	v_pk_add_f32 v[150:151], v[150:151], v[152:153]
	s_nop 0
	v_pk_add_f32 v[150:151], v[156:157], v[150:151]
	ds_bpermute_b32 v152, v200, v150
	ds_bpermute_b32 v153, v200, v151
	s_waitcnt lgkmcnt(0)
	v_pk_add_f32 v[150:151], v[150:151], v[152:153]
	ds_bpermute_b32 v152, v199, v150
	ds_bpermute_b32 v153, v199, v151
	s_and_saveexec_b64 s[4:5], vcc
	s_cbranch_execz .LBB0_1743
	s_waitcnt lgkmcnt(0)
	v_pk_add_f32 v[150:151], v[150:151], v[152:153]
	v_lshl_add_u32 v152, v154, 5, s97
	ds_write_b64 v152, v[150:151]
.LBB0_1743:
	s_or_b64 exec, exec, s[4:5]
	s_waitcnt lgkmcnt(1)
	v_add_u32_e32 v152, 0x90, v128
	s_waitcnt lgkmcnt(0)
	v_ashrrev_i32_e32 v153, 31, v152
	v_lshlrev_b64 v[150:151], 13, v[152:153]
	v_lshl_add_u64 v[150:151], s[68:69], 0, v[150:151]
	v_lshl_add_u64 v[150:151], v[130:131], 2, v[150:151]
	s_waitcnt vmcnt(11)
	v_pk_fma_f32 v[46:47], v[236:237], s[96:97], v[46:47] op_sel_hi:[1,0,1]
	v_pk_fma_f32 v[44:45], v[234:235], s[96:97], v[44:45] op_sel_hi:[1,0,1]
	v_add_f32_e32 v158, v44, v45
	v_add_f32_e32 v160, v46, v47
	v_mul_f32_e32 v163, v44, v44
	v_mul_f32_e32 v165, v45, v45
	v_mul_f32_e32 v167, v46, v46
	v_mul_f32_e32 v169, v47, v47
	s_waitcnt vmcnt(10)
	v_pk_fma_f32 v[42:43], v[240:241], s[96:97], v[42:43] op_sel_hi:[1,0,1]
	v_pk_fma_f32 v[40:41], v[238:239], s[96:97], v[40:41] op_sel_hi:[1,0,1]
	v_mul_f32_e32 v154, v42, v42
	v_pk_fma_f32 v[170:171], v[42:43], v[42:43], v[154:155] op_sel_hi:[1,1,0]
	v_mul_f32_e32 v159, v40, v40
	v_mul_f32_e32 v161, v41, v41
	v_mov_b32_e32 v162, v40
	v_mov_b32_e32 v164, v41
	v_mov_b32_e32 v166, v42
	v_mov_b32_e32 v168, v43
	v_pk_add_f32 v[162:163], v[162:163], v[164:165]
	v_pk_add_f32 v[164:165], v[166:167], v[168:169]
	v_pk_add_f32 v[158:159], v[158:159], v[160:161]
	v_mov_b32_e32 v170, v129
	v_pk_add_f32 v[162:163], v[162:163], v[164:165]
	v_pk_add_f32 v[158:159], v[158:159], v[170:171]
	s_waitcnt vmcnt(9)
	v_pk_fma_f32 v[38:39], v[244:245], s[96:97], v[38:39] op_sel_hi:[1,0,1]
	v_pk_fma_f32 v[36:37], v[242:243], s[96:97], v[36:37] op_sel_hi:[1,0,1]
	v_mul_f32_e32 v173, v36, v36
	v_mul_f32_e32 v175, v37, v37
	v_mul_f32_e32 v177, v38, v38
	v_mul_f32_e32 v179, v39, v39
	v_mov_b32_e32 v172, v36
	v_mov_b32_e32 v174, v37
	v_mov_b32_e32 v176, v38
	v_mov_b32_e32 v178, v39
	v_pk_add_f32 v[158:159], v[162:163], v[158:159]
	v_pk_add_f32 v[160:161], v[172:173], v[174:175]
	v_pk_add_f32 v[162:163], v[176:177], v[178:179]
	s_waitcnt vmcnt(8)
	v_pk_fma_f32 v[34:35], v[248:249], s[96:97], v[34:35] op_sel_hi:[1,0,1]
	v_pk_fma_f32 v[32:33], v[246:247], s[96:97], v[32:33] op_sel_hi:[1,0,1]
	v_mul_f32_e32 v181, v34, v34
	v_mul_f32_e32 v155, v32, v32
	v_mul_f32_e32 v157, v33, v33
	v_mul_f32_e32 v183, v35, v35
	v_mov_b32_e32 v154, v32
	v_mov_b32_e32 v156, v33
	v_mov_b32_e32 v180, v34
	v_mov_b32_e32 v182, v35
	v_pk_add_f32 v[160:161], v[160:161], v[162:163]
	v_pk_add_f32 v[154:155], v[154:155], v[156:157]
	v_pk_add_f32 v[156:157], v[180:181], v[182:183]
	v_pk_add_f32 v[158:159], v[158:159], v[160:161]
	v_pk_add_f32 v[154:155], v[154:155], v[156:157]
	s_nop 0
	v_pk_add_f32 v[154:155], v[158:159], v[154:155]
	ds_bpermute_b32 v156, v200, v154
	ds_bpermute_b32 v157, v200, v155
	s_waitcnt lgkmcnt(0)
	v_pk_add_f32 v[154:155], v[154:155], v[156:157]
	ds_bpermute_b32 v156, v199, v154
	ds_bpermute_b32 v157, v199, v155
	s_and_saveexec_b64 s[4:5], vcc
	s_cbranch_execz .LBB0_1745
	s_waitcnt lgkmcnt(0)
	v_pk_add_f32 v[154:155], v[154:155], v[156:157]
	ds_write_b64 v201, v[154:155] offset:4608
.LBB0_1745:
	s_or_b64 exec, exec, s[4:5]
	s_waitcnt lgkmcnt(1)
	v_add_u32_e32 v156, 0xa0, v128
	s_waitcnt lgkmcnt(0)
	v_ashrrev_i32_e32 v157, 31, v156
	v_lshlrev_b64 v[154:155], 13, v[156:157]
	v_lshl_add_u64 v[154:155], s[68:69], 0, v[154:155]
	v_lshl_add_u64 v[154:155], v[130:131], 2, v[154:155]
	s_waitcnt vmcnt(7)
	v_pk_fma_f32 v[160:161], v[204:205], s[96:97], v[30:31] op_sel_hi:[1,0,1]
	v_pk_fma_f32 v[158:159], v[202:203], s[96:97], v[28:29] op_sel_hi:[1,0,1]
	v_add_f32_e32 v174, v158, v159
	v_add_f32_e32 v176, v160, v161
	v_mul_f32_e32 v179, v158, v158
	v_mul_f32_e32 v181, v159, v159
	v_mul_f32_e32 v183, v160, v160
	v_mul_f32_e32 v185, v161, v161
	s_waitcnt vmcnt(6)
	v_pk_fma_f32 v[164:165], v[208:209], s[96:97], v[26:27] op_sel_hi:[1,0,1]
	v_pk_fma_f32 v[162:163], v[206:207], s[96:97], v[24:25] op_sel_hi:[1,0,1]
	v_mul_f32_e32 v24, v164, v164
	v_pk_fma_f32 v[28:29], v[164:165], v[164:165], v[24:25] op_sel_hi:[1,1,0]
	v_mul_f32_e32 v175, v162, v162
	v_mul_f32_e32 v177, v163, v163
	v_mov_b32_e32 v178, v162
	v_mov_b32_e32 v180, v163
	v_mov_b32_e32 v182, v164
	v_mov_b32_e32 v184, v165
	v_pk_add_f32 v[178:179], v[178:179], v[180:181]
	v_pk_add_f32 v[180:181], v[182:183], v[184:185]
	v_pk_add_f32 v[174:175], v[174:175], v[176:177]
	v_mov_b32_e32 v28, v129
	v_pk_add_f32 v[178:179], v[178:179], v[180:181]
	v_pk_add_f32 v[28:29], v[174:175], v[28:29]
	s_waitcnt vmcnt(5)
	v_pk_fma_f32 v[168:169], v[212:213], s[96:97], v[22:23] op_sel_hi:[1,0,1]
	v_pk_fma_f32 v[166:167], v[210:211], s[96:97], v[20:21] op_sel_hi:[1,0,1]
	v_mul_f32_e32 v25, v166, v166
	v_mul_f32_e32 v27, v167, v167
	v_mul_f32_e32 v31, v168, v168
	v_mul_f32_e32 v187, v169, v169
	v_mov_b32_e32 v24, v166
	v_mov_b32_e32 v26, v167
	v_mov_b32_e32 v30, v168
	v_mov_b32_e32 v186, v169
	v_pk_add_f32 v[24:25], v[24:25], v[26:27]
	v_pk_add_f32 v[26:27], v[30:31], v[186:187]
	v_pk_add_f32 v[28:29], v[178:179], v[28:29]
	v_pk_add_f32 v[24:25], v[24:25], v[26:27]
	s_waitcnt vmcnt(4)
	v_pk_fma_f32 v[172:173], v[216:217], s[96:97], v[18:19] op_sel_hi:[1,0,1]
	v_pk_fma_f32 v[170:171], v[214:215], s[96:97], v[16:17] op_sel_hi:[1,0,1]
	v_mul_f32_e32 v21, v172, v172
	v_mul_f32_e32 v17, v170, v170
	v_mul_f32_e32 v19, v171, v171
	v_mul_f32_e32 v23, v173, v173
	v_mov_b32_e32 v16, v170
	v_mov_b32_e32 v18, v171
	v_mov_b32_e32 v20, v172
	v_mov_b32_e32 v22, v173
	v_pk_add_f32 v[16:17], v[16:17], v[18:19]
	v_pk_add_f32 v[18:19], v[20:21], v[22:23]
	v_pk_add_f32 v[24:25], v[28:29], v[24:25]
	v_pk_add_f32 v[16:17], v[16:17], v[18:19]
	s_nop 0
	v_pk_add_f32 v[16:17], v[24:25], v[16:17]
	ds_bpermute_b32 v18, v200, v16
	ds_bpermute_b32 v19, v200, v17
	s_waitcnt lgkmcnt(0)
	v_pk_add_f32 v[16:17], v[16:17], v[18:19]
	ds_bpermute_b32 v18, v199, v16
	ds_bpermute_b32 v19, v199, v17
	s_and_saveexec_b64 s[4:5], vcc
	s_cbranch_execz .LBB0_1747
	s_waitcnt lgkmcnt(0)
	v_pk_add_f32 v[16:17], v[16:17], v[18:19]
	ds_write_b64 v201, v[16:17] offset:5120
.LBB0_1747:
	s_or_b64 exec, exec, s[4:5]
	v_add_u32_e32 v176, 0xb0, v128
	v_ashrrev_i32_e32 v177, 31, v176
	v_lshlrev_b64 v[16:17], 13, v[176:177]
	v_lshl_add_u64 v[16:17], s[68:69], 0, v[16:17]
	v_lshl_add_u64 v[174:175], v[130:131], 2, v[16:17]
	s_waitcnt lgkmcnt(0)
	s_waitcnt vmcnt(3)
	v_pk_fma_f32 v[180:181], v[220:221], s[96:97], v[14:15] op_sel_hi:[1,0,1]
	v_pk_fma_f32 v[178:179], v[218:219], s[96:97], v[12:13] op_sel_hi:[1,0,1]
	v_add_f32_e32 v16, v178, v179
	v_add_f32_e32 v18, v180, v181
	v_mul_f32_e32 v21, v178, v178
	v_mul_f32_e32 v23, v179, v179
	v_mul_f32_e32 v25, v180, v180
	v_mul_f32_e32 v27, v181, v181
	s_waitcnt vmcnt(2)
	v_pk_fma_f32 v[184:185], v[224:225], s[96:97], v[10:11] op_sel_hi:[1,0,1]
	v_pk_fma_f32 v[182:183], v[222:223], s[96:97], v[8:9] op_sel_hi:[1,0,1]
	v_mul_f32_e32 v8, v184, v184
	v_pk_fma_f32 v[12:13], v[184:185], v[184:185], v[8:9] op_sel_hi:[1,1,0]
	v_mul_f32_e32 v17, v182, v182
	v_mul_f32_e32 v19, v183, v183
	v_mov_b32_e32 v20, v182
	v_mov_b32_e32 v22, v183
	v_mov_b32_e32 v24, v184
	v_mov_b32_e32 v26, v185
	v_pk_add_f32 v[20:21], v[20:21], v[22:23]
	v_pk_add_f32 v[22:23], v[24:25], v[26:27]
	v_pk_add_f32 v[16:17], v[16:17], v[18:19]
	v_mov_b32_e32 v12, v129
	v_pk_add_f32 v[20:21], v[20:21], v[22:23]
	v_pk_add_f32 v[12:13], v[16:17], v[12:13]
	s_waitcnt vmcnt(1)
	v_pk_fma_f32 v[188:189], v[228:229], s[96:97], v[6:7] op_sel_hi:[1,0,1]
	v_pk_fma_f32 v[186:187], v[226:227], s[96:97], v[4:5] op_sel_hi:[1,0,1]
	v_mul_f32_e32 v9, v186, v186
	v_mul_f32_e32 v11, v187, v187
	v_mul_f32_e32 v15, v188, v188
	v_mul_f32_e32 v29, v189, v189
	v_mov_b32_e32 v8, v186
	v_mov_b32_e32 v10, v187
	v_mov_b32_e32 v14, v188
	v_mov_b32_e32 v28, v189
	v_pk_add_f32 v[8:9], v[8:9], v[10:11]
	v_pk_add_f32 v[10:11], v[14:15], v[28:29]
	v_pk_add_f32 v[12:13], v[20:21], v[12:13]
	v_pk_add_f32 v[8:9], v[8:9], v[10:11]
	s_waitcnt vmcnt(0)
	v_pk_fma_f32 v[192:193], v[232:233], s[96:97], v[2:3] op_sel_hi:[1,0,1]
	v_pk_fma_f32 v[190:191], v[230:231], s[96:97], v[0:1] op_sel_hi:[1,0,1]
	v_mul_f32_e32 v5, v192, v192
	v_mul_f32_e32 v1, v190, v190
	v_mul_f32_e32 v3, v191, v191
	v_mul_f32_e32 v7, v193, v193
	v_mov_b32_e32 v0, v190
	v_mov_b32_e32 v2, v191
	v_mov_b32_e32 v4, v192
	v_mov_b32_e32 v6, v193
	v_pk_add_f32 v[0:1], v[0:1], v[2:3]
	v_pk_add_f32 v[2:3], v[4:5], v[6:7]
	v_pk_add_f32 v[8:9], v[12:13], v[8:9]
	v_pk_add_f32 v[0:1], v[0:1], v[2:3]
	s_nop 0
	v_pk_add_f32 v[0:1], v[8:9], v[0:1]
	ds_bpermute_b32 v2, v200, v0
	ds_bpermute_b32 v3, v200, v1
	s_waitcnt lgkmcnt(0)
	v_pk_add_f32 v[0:1], v[0:1], v[2:3]
	ds_bpermute_b32 v2, v199, v0
	ds_bpermute_b32 v3, v199, v1
	s_and_saveexec_b64 s[4:5], vcc
	s_cbranch_execz .LBB0_1749
	s_waitcnt lgkmcnt(0)
	v_pk_add_f32 v[0:1], v[0:1], v[2:3]
	ds_write_b64 v201, v[0:1] offset:5632

.LBB0_2066:
	v_ashrrev_i32_e32 v128, 2, v184
	v_and_b32_e32 v128, -4, v128
	v_and_b32_e32 v130, 64, v180
	v_add_u32_e32 v132, s11, v128
	v_xor_b32_e32 v128, 16, v180
	v_add_u32_e32 v130, 64, v130
	v_cmp_lt_i32_e32 vcc, v128, v130
	s_lshl_b32 s4, s0, 8
	v_ashrrev_i32_e32 v133, 31, v132
	v_cndmask_b32_e32 v128, v180, v128, vcc
	v_lshlrev_b32_e32 v186, 2, v128
	v_xor_b32_e32 v128, 32, v180
	v_cmp_lt_i32_e32 vcc, v128, v130
	s_barrier
	v_lshl_add_u32 v187, v183, 5, s12
	v_cndmask_b32_e32 v128, v180, v128, vcc
	v_lshlrev_b32_e32 v185, 2, v128
	v_add_u32_e32 v128, s4, v183
	v_lshlrev_b64 v[130:131], 13, v[128:129]
	v_lshl_add_u64 v[130:131], s[68:69], 0, v[130:131]
	v_lshl_add_u64 v[130:131], v[132:133], 2, v[130:131]
	v_mov_b64_e32 v[252:253], v[130:131]
	global_load_dwordx4 v[202:205], v[252:253], off
	global_load_dwordx4 v[206:209], v[252:253], off offset:64
	global_load_dwordx4 v[210:213], v[252:253], off offset:512
	global_load_dwordx4 v[214:217], v[252:253], off offset:576
	s_mov_b32 s98, 0x20000
	s_mov_b32 s99, 0
	v_lshl_add_u64 v[254:255], v[252:253], 0, s[98:99]
	global_load_dwordx4 v[218:221], v[254:255], off
	global_load_dwordx4 v[222:225], v[254:255], off offset:64
	global_load_dwordx4 v[226:229], v[254:255], off offset:512
	global_load_dwordx4 v[230:233], v[254:255], off offset:576
	s_mov_b32 s98, 0x40000
	s_mov_b32 s99, 0
	v_lshl_add_u64 v[254:255], v[252:253], 0, s[98:99]
	global_load_dwordx4 v[234:237], v[254:255], off
	global_load_dwordx4 v[238:241], v[254:255], off offset:64
	global_load_dwordx4 v[242:245], v[254:255], off offset:512
	global_load_dwordx4 v[246:249], v[254:255], off offset:576
	v_cmp_gt_u32_e32 vcc, 16, v184
	s_waitcnt vmcnt(11)
	v_pk_fma_f32 v[126:127], v[204:205], s[88:89], v[126:127] op_sel_hi:[1,0,1]
	v_pk_fma_f32 v[124:125], v[202:203], s[88:89], v[124:125] op_sel_hi:[1,0,1]
	v_add_f32_e32 v138, v124, v125
	v_add_f32_e32 v140, v126, v127
	v_mul_f32_e32 v143, v124, v124
	v_mul_f32_e32 v145, v125, v125
	v_mul_f32_e32 v147, v126, v126
	v_mul_f32_e32 v149, v127, v127
	s_waitcnt vmcnt(10)
	v_pk_fma_f32 v[122:123], v[208:209], s[88:89], v[122:123] op_sel_hi:[1,0,1]
	v_pk_fma_f32 v[120:121], v[206:207], s[88:89], v[120:121] op_sel_hi:[1,0,1]
	v_mul_f32_e32 v134, v122, v122
	v_pk_fma_f32 v[150:151], v[122:123], v[122:123], v[134:135] op_sel_hi:[1,1,0]
	v_mul_f32_e32 v139, v120, v120
	v_mul_f32_e32 v141, v121, v121
	v_mov_b32_e32 v142, v120
	v_mov_b32_e32 v144, v121
	v_mov_b32_e32 v146, v122
	v_mov_b32_e32 v148, v123
	v_pk_add_f32 v[142:143], v[142:143], v[144:145]
	v_pk_add_f32 v[144:145], v[146:147], v[148:149]
	v_pk_add_f32 v[138:139], v[138:139], v[140:141]
	v_mov_b32_e32 v150, v129
	v_pk_add_f32 v[142:143], v[142:143], v[144:145]
	v_pk_add_f32 v[138:139], v[138:139], v[150:151]
	s_waitcnt vmcnt(9)
	v_pk_fma_f32 v[118:119], v[212:213], s[88:89], v[118:119] op_sel_hi:[1,0,1]
	v_pk_fma_f32 v[116:117], v[210:211], s[88:89], v[116:117] op_sel_hi:[1,0,1]
	v_mul_f32_e32 v153, v116, v116
	v_mul_f32_e32 v155, v117, v117
	v_mul_f32_e32 v157, v118, v118
	v_mul_f32_e32 v159, v119, v119
	v_mov_b32_e32 v152, v116
	v_mov_b32_e32 v154, v117
	v_mov_b32_e32 v156, v118
	v_mov_b32_e32 v158, v119
	v_pk_add_f32 v[138:139], v[142:143], v[138:139]
	v_pk_add_f32 v[140:141], v[152:153], v[154:155]
	v_pk_add_f32 v[142:143], v[156:157], v[158:159]
	s_waitcnt vmcnt(8)
	v_pk_fma_f32 v[114:115], v[216:217], s[88:89], v[114:115] op_sel_hi:[1,0,1]
	v_pk_fma_f32 v[112:113], v[214:215], s[88:89], v[112:113] op_sel_hi:[1,0,1]
	s_mov_b32 s98, 0x60000
	s_mov_b32 s99, 0
	v_lshl_add_u64 v[254:255], v[252:253], 0, s[98:99]
	global_load_dwordx4 v[202:205], v[254:255], off
	global_load_dwordx4 v[206:209], v[254:255], off offset:64
	global_load_dwordx4 v[210:213], v[254:255], off offset:512
	global_load_dwordx4 v[214:217], v[254:255], off offset:576
	v_mul_f32_e32 v161, v114, v114
	v_mul_f32_e32 v135, v112, v112
	v_mul_f32_e32 v137, v113, v113
	v_mul_f32_e32 v163, v115, v115
	v_mov_b32_e32 v134, v112
	v_mov_b32_e32 v136, v113
	v_mov_b32_e32 v160, v114
	v_mov_b32_e32 v162, v115
	v_pk_add_f32 v[140:141], v[140:141], v[142:143]
	v_pk_add_f32 v[134:135], v[134:135], v[136:137]
	v_pk_add_f32 v[136:137], v[160:161], v[162:163]
	v_pk_add_f32 v[138:139], v[138:139], v[140:141]
	v_pk_add_f32 v[134:135], v[134:135], v[136:137]
	s_nop 0
	v_pk_add_f32 v[134:135], v[138:139], v[134:135]
	ds_bpermute_b32 v136, v186, v134
	ds_bpermute_b32 v137, v186, v135
	s_waitcnt lgkmcnt(0)
	v_pk_add_f32 v[134:135], v[134:135], v[136:137]
	ds_bpermute_b32 v136, v185, v134
	ds_bpermute_b32 v137, v185, v135
	s_and_saveexec_b64 s[0:1], vcc
	s_cbranch_execz .LBB0_2068
	s_waitcnt lgkmcnt(0)
	v_pk_add_f32 v[134:135], v[134:135], v[136:137]
	ds_write_b64 v187, v[134:135]
.LBB0_2068:
	s_or_b64 exec, exec, s[0:1]
	v_or_b32_e32 v140, 16, v183
	v_add_u32_e32 v134, s4, v140
	v_mov_b32_e32 v135, v129
	v_lshlrev_b64 v[134:135], 13, v[134:135]
	v_lshl_add_u64 v[134:135], s[68:69], 0, v[134:135]
	v_lshl_add_u64 v[134:135], v[132:133], 2, v[134:135]
	s_waitcnt lgkmcnt(0)
	s_waitcnt vmcnt(11)
	v_pk_fma_f32 v[110:111], v[220:221], s[88:89], v[110:111] op_sel_hi:[1,0,1]
	v_pk_fma_f32 v[108:109], v[218:219], s[88:89], v[108:109] op_sel_hi:[1,0,1]
	v_add_f32_e32 v142, v108, v109
	v_add_f32_e32 v144, v110, v111
	v_mul_f32_e32 v147, v108, v108
	v_mul_f32_e32 v149, v109, v109
	v_mul_f32_e32 v151, v110, v110
	v_mul_f32_e32 v153, v111, v111
	s_waitcnt vmcnt(10)
	v_pk_fma_f32 v[106:107], v[224:225], s[88:89], v[106:107] op_sel_hi:[1,0,1]
	v_pk_fma_f32 v[104:105], v[222:223], s[88:89], v[104:105] op_sel_hi:[1,0,1]
	v_mul_f32_e32 v136, v106, v106
	v_pk_fma_f32 v[154:155], v[106:107], v[106:107], v[136:137] op_sel_hi:[1,1,0]
	v_mul_f32_e32 v143, v104, v104
	v_mul_f32_e32 v145, v105, v105
	v_mov_b32_e32 v146, v104
	v_mov_b32_e32 v148, v105
	v_mov_b32_e32 v150, v106
	v_mov_b32_e32 v152, v107
	v_pk_add_f32 v[146:147], v[146:147], v[148:149]
	v_pk_add_f32 v[148:149], v[150:151], v[152:153]
	v_pk_add_f32 v[142:143], v[142:143], v[144:145]
	v_mov_b32_e32 v154, v129
	v_pk_add_f32 v[146:147], v[146:147], v[148:149]
	v_pk_add_f32 v[142:143], v[142:143], v[154:155]
	s_waitcnt vmcnt(9)
	v_pk_fma_f32 v[102:103], v[228:229], s[88:89], v[102:103] op_sel_hi:[1,0,1]
	v_pk_fma_f32 v[100:101], v[226:227], s[88:89], v[100:101] op_sel_hi:[1,0,1]
	v_mul_f32_e32 v157, v100, v100
	v_mul_f32_e32 v159, v101, v101
	v_mul_f32_e32 v161, v102, v102
	v_mul_f32_e32 v163, v103, v103
	v_mov_b32_e32 v156, v100
	v_mov_b32_e32 v158, v101
	v_mov_b32_e32 v160, v102
	v_mov_b32_e32 v162, v103
	v_pk_add_f32 v[142:143], v[146:147], v[142:143]
	v_pk_add_f32 v[144:145], v[156:157], v[158:159]
	v_pk_add_f32 v[146:147], v[160:161], v[162:163]
	s_waitcnt vmcnt(8)
	v_pk_fma_f32 v[98:99], v[232:233], s[88:89], v[98:99] op_sel_hi:[1,0,1]
	v_pk_fma_f32 v[96:97], v[230:231], s[88:89], v[96:97] op_sel_hi:[1,0,1]
	s_mov_b32 s98, 0x100000
	s_mov_b32 s99, 0
	v_lshl_add_u64 v[254:255], v[252:253], 0, s[98:99]
	global_load_dwordx4 v[218:221], v[254:255], off
	global_load_dwordx4 v[222:225], v[254:255], off offset:64
	global_load_dwordx4 v[226:229], v[254:255], off offset:512
	global_load_dwordx4 v[230:233], v[254:255], off offset:576
	v_mul_f32_e32 v165, v98, v98
	v_mul_f32_e32 v137, v96, v96
	v_mul_f32_e32 v139, v97, v97
	v_mul_f32_e32 v167, v99, v99
	v_mov_b32_e32 v136, v96
	v_mov_b32_e32 v138, v97
	v_mov_b32_e32 v164, v98
	v_mov_b32_e32 v166, v99
	v_pk_add_f32 v[144:145], v[144:145], v[146:147]
	v_pk_add_f32 v[136:137], v[136:137], v[138:139]
	v_pk_add_f32 v[138:139], v[164:165], v[166:167]
	v_pk_add_f32 v[142:143], v[142:143], v[144:145]
	v_pk_add_f32 v[136:137], v[136:137], v[138:139]
	s_nop 0
	v_pk_add_f32 v[136:137], v[142:143], v[136:137]
	ds_bpermute_b32 v138, v186, v136
	ds_bpermute_b32 v139, v186, v137
	s_waitcnt lgkmcnt(0)
	v_pk_add_f32 v[136:137], v[136:137], v[138:139]
	ds_bpermute_b32 v138, v185, v136
	ds_bpermute_b32 v139, v185, v137
	s_and_saveexec_b64 s[0:1], vcc
	s_cbranch_execz .LBB0_2070
	s_waitcnt lgkmcnt(0)
	v_pk_add_f32 v[136:137], v[136:137], v[138:139]
	v_lshl_add_u32 v138, v140, 5, s12
	ds_write_b64 v138, v[136:137]
.LBB0_2070:
	s_or_b64 exec, exec, s[0:1]
	v_or_b32_e32 v142, 32, v183
	v_add_u32_e32 v136, s4, v142
	v_mov_b32_e32 v137, v129
	v_lshlrev_b64 v[136:137], 13, v[136:137]
	v_lshl_add_u64 v[136:137], s[68:69], 0, v[136:137]
	v_lshl_add_u64 v[136:137], v[132:133], 2, v[136:137]
	s_waitcnt lgkmcnt(0)
	s_waitcnt vmcnt(11)
	v_pk_fma_f32 v[94:95], v[236:237], s[88:89], v[94:95] op_sel_hi:[1,0,1]
	v_pk_fma_f32 v[92:93], v[234:235], s[88:89], v[92:93] op_sel_hi:[1,0,1]
	v_add_f32_e32 v144, v92, v93
	v_add_f32_e32 v146, v94, v95
	v_mul_f32_e32 v149, v92, v92
	v_mul_f32_e32 v151, v93, v93
	v_mul_f32_e32 v153, v94, v94
	v_mul_f32_e32 v155, v95, v95
	s_waitcnt vmcnt(10)
	v_pk_fma_f32 v[90:91], v[240:241], s[88:89], v[90:91] op_sel_hi:[1,0,1]
	v_pk_fma_f32 v[88:89], v[238:239], s[88:89], v[88:89] op_sel_hi:[1,0,1]
	v_mul_f32_e32 v138, v90, v90
	v_pk_fma_f32 v[156:157], v[90:91], v[90:91], v[138:139] op_sel_hi:[1,1,0]
	v_mul_f32_e32 v145, v88, v88
	v_mul_f32_e32 v147, v89, v89
	v_mov_b32_e32 v148, v88
	v_mov_b32_e32 v150, v89
	v_mov_b32_e32 v152, v90
	v_mov_b32_e32 v154, v91
	v_pk_add_f32 v[148:149], v[148:149], v[150:151]
	v_pk_add_f32 v[150:151], v[152:153], v[154:155]
	v_pk_add_f32 v[144:145], v[144:145], v[146:147]
	v_mov_b32_e32 v156, v129
	v_pk_add_f32 v[148:149], v[148:149], v[150:151]
	v_pk_add_f32 v[144:145], v[144:145], v[156:157]
	s_waitcnt vmcnt(9)
	v_pk_fma_f32 v[86:87], v[244:245], s[88:89], v[86:87] op_sel_hi:[1,0,1]
	v_pk_fma_f32 v[84:85], v[242:243], s[88:89], v[84:85] op_sel_hi:[1,0,1]
	v_mul_f32_e32 v159, v84, v84
	v_mul_f32_e32 v161, v85, v85
	v_mul_f32_e32 v163, v86, v86
	v_mul_f32_e32 v165, v87, v87
	v_mov_b32_e32 v158, v84
	v_mov_b32_e32 v160, v85
	v_mov_b32_e32 v162, v86
	v_mov_b32_e32 v164, v87
	v_pk_add_f32 v[144:145], v[148:149], v[144:145]
	v_pk_add_f32 v[146:147], v[158:159], v[160:161]
	v_pk_add_f32 v[148:149], v[162:163], v[164:165]
	s_waitcnt vmcnt(8)
	v_pk_fma_f32 v[82:83], v[248:249], s[88:89], v[82:83] op_sel_hi:[1,0,1]
	v_pk_fma_f32 v[80:81], v[246:247], s[88:89], v[80:81] op_sel_hi:[1,0,1]
	s_mov_b32 s98, 0x120000
	s_mov_b32 s99, 0
	v_lshl_add_u64 v[254:255], v[252:253], 0, s[98:99]
	global_load_dwordx4 v[234:237], v[254:255], off
	global_load_dwordx4 v[238:241], v[254:255], off offset:64
	global_load_dwordx4 v[242:245], v[254:255], off offset:512
	global_load_dwordx4 v[246:249], v[254:255], off offset:576
	v_mul_f32_e32 v167, v82, v82
	v_mul_f32_e32 v139, v80, v80
	v_mul_f32_e32 v141, v81, v81
	v_mul_f32_e32 v169, v83, v83
	v_mov_b32_e32 v138, v80
	v_mov_b32_e32 v140, v81
	v_mov_b32_e32 v166, v82
	v_mov_b32_e32 v168, v83
	v_pk_add_f32 v[146:147], v[146:147], v[148:149]
	v_pk_add_f32 v[138:139], v[138:139], v[140:141]
	v_pk_add_f32 v[140:141], v[166:167], v[168:169]
	v_pk_add_f32 v[144:145], v[144:145], v[146:147]
	v_pk_add_f32 v[138:139], v[138:139], v[140:141]
	s_nop 0
	v_pk_add_f32 v[138:139], v[144:145], v[138:139]
	ds_bpermute_b32 v140, v186, v138
	ds_bpermute_b32 v141, v186, v139
	s_waitcnt lgkmcnt(0)
	v_pk_add_f32 v[138:139], v[138:139], v[140:141]
	ds_bpermute_b32 v140, v185, v138
	ds_bpermute_b32 v141, v185, v139
	s_and_saveexec_b64 s[0:1], vcc
	s_cbranch_execz .LBB0_2072
	s_waitcnt lgkmcnt(0)
	v_pk_add_f32 v[138:139], v[138:139], v[140:141]
	v_lshl_add_u32 v140, v142, 5, s12
	ds_write_b64 v140, v[138:139]
.LBB0_2072:
	s_or_b64 exec, exec, s[0:1]
	v_or_b32_e32 v144, 48, v183
	v_add_u32_e32 v138, s4, v144
	v_mov_b32_e32 v139, v129
	v_lshlrev_b64 v[138:139], 13, v[138:139]
	v_lshl_add_u64 v[138:139], s[68:69], 0, v[138:139]
	v_lshl_add_u64 v[138:139], v[132:133], 2, v[138:139]
	s_waitcnt lgkmcnt(0)
	s_waitcnt vmcnt(11)
	v_pk_fma_f32 v[78:79], v[204:205], s[88:89], v[78:79] op_sel_hi:[1,0,1]
	v_pk_fma_f32 v[76:77], v[202:203], s[88:89], v[76:77] op_sel_hi:[1,0,1]
	v_add_f32_e32 v146, v76, v77
	v_add_f32_e32 v148, v78, v79
	v_mul_f32_e32 v151, v76, v76
	v_mul_f32_e32 v153, v77, v77
	v_mul_f32_e32 v155, v78, v78
	v_mul_f32_e32 v157, v79, v79
	s_waitcnt vmcnt(10)
	v_pk_fma_f32 v[74:75], v[208:209], s[88:89], v[74:75] op_sel_hi:[1,0,1]
	v_pk_fma_f32 v[72:73], v[206:207], s[88:89], v[72:73] op_sel_hi:[1,0,1]
	v_mul_f32_e32 v140, v74, v74
	v_pk_fma_f32 v[158:159], v[74:75], v[74:75], v[140:141] op_sel_hi:[1,1,0]
	v_mul_f32_e32 v147, v72, v72
	v_mul_f32_e32 v149, v73, v73
	v_mov_b32_e32 v150, v72
	v_mov_b32_e32 v152, v73
	v_mov_b32_e32 v154, v74
	v_mov_b32_e32 v156, v75
	v_pk_add_f32 v[150:151], v[150:151], v[152:153]
	v_pk_add_f32 v[152:153], v[154:155], v[156:157]
	v_pk_add_f32 v[146:147], v[146:147], v[148:149]
	v_mov_b32_e32 v158, v129
	v_pk_add_f32 v[150:151], v[150:151], v[152:153]
	v_pk_add_f32 v[146:147], v[146:147], v[158:159]
	s_waitcnt vmcnt(9)
	v_pk_fma_f32 v[70:71], v[212:213], s[88:89], v[70:71] op_sel_hi:[1,0,1]
	v_pk_fma_f32 v[68:69], v[210:211], s[88:89], v[68:69] op_sel_hi:[1,0,1]
	v_mul_f32_e32 v161, v68, v68
	v_mul_f32_e32 v163, v69, v69
	v_mul_f32_e32 v165, v70, v70
	v_mul_f32_e32 v167, v71, v71
	v_mov_b32_e32 v160, v68
	v_mov_b32_e32 v162, v69
	v_mov_b32_e32 v164, v70
	v_mov_b32_e32 v166, v71
	v_pk_add_f32 v[146:147], v[150:151], v[146:147]
	v_pk_add_f32 v[148:149], v[160:161], v[162:163]
	v_pk_add_f32 v[150:151], v[164:165], v[166:167]
	s_waitcnt vmcnt(8)
	v_pk_fma_f32 v[66:67], v[216:217], s[88:89], v[66:67] op_sel_hi:[1,0,1]
	v_pk_fma_f32 v[64:65], v[214:215], s[88:89], v[64:65] op_sel_hi:[1,0,1]
	s_mov_b32 s98, 0x140000
	s_mov_b32 s99, 0
	v_lshl_add_u64 v[254:255], v[252:253], 0, s[98:99]
	global_load_dwordx4 v[202:205], v[254:255], off
	global_load_dwordx4 v[206:209], v[254:255], off offset:64
	global_load_dwordx4 v[210:213], v[254:255], off offset:512
	global_load_dwordx4 v[214:217], v[254:255], off offset:576
	v_mul_f32_e32 v169, v66, v66
	v_mul_f32_e32 v141, v64, v64
	v_mul_f32_e32 v143, v65, v65
	v_mul_f32_e32 v171, v67, v67
	v_mov_b32_e32 v140, v64
	v_mov_b32_e32 v142, v65
	v_mov_b32_e32 v168, v66
	v_mov_b32_e32 v170, v67
	v_pk_add_f32 v[148:149], v[148:149], v[150:151]
	v_pk_add_f32 v[140:141], v[140:141], v[142:143]
	v_pk_add_f32 v[142:143], v[168:169], v[170:171]
	v_pk_add_f32 v[146:147], v[146:147], v[148:149]
	v_pk_add_f32 v[140:141], v[140:141], v[142:143]
	s_nop 0
	v_pk_add_f32 v[140:141], v[146:147], v[140:141]
	ds_bpermute_b32 v142, v186, v140
	ds_bpermute_b32 v143, v186, v141
	s_waitcnt lgkmcnt(0)
	v_pk_add_f32 v[140:141], v[140:141], v[142:143]
	ds_bpermute_b32 v142, v185, v140
	ds_bpermute_b32 v143, v185, v141
	s_and_saveexec_b64 s[0:1], vcc
	s_cbranch_execz .LBB0_2074
	s_waitcnt lgkmcnt(0)
	v_pk_add_f32 v[140:141], v[140:141], v[142:143]
	v_lshl_add_u32 v142, v144, 5, s12
	ds_write_b64 v142, v[140:141]
.LBB0_2074:
	s_or_b64 exec, exec, s[0:1]
	v_add_u32_e32 v146, 0x80, v183
	v_add_u32_e32 v140, s4, v146
	v_ashrrev_i32_e32 v141, 31, v140
	v_lshlrev_b64 v[140:141], 13, v[140:141]
	v_lshl_add_u64 v[140:141], s[68:69], 0, v[140:141]
	v_lshl_add_u64 v[140:141], v[132:133], 2, v[140:141]
	s_waitcnt lgkmcnt(0)
	s_waitcnt vmcnt(11)
	v_pk_fma_f32 v[62:63], v[220:221], s[88:89], v[62:63] op_sel_hi:[1,0,1]
	v_pk_fma_f32 v[60:61], v[218:219], s[88:89], v[60:61] op_sel_hi:[1,0,1]
	v_add_f32_e32 v148, v60, v61
	v_add_f32_e32 v150, v62, v63
	v_mul_f32_e32 v153, v60, v60
	v_mul_f32_e32 v155, v61, v61
	v_mul_f32_e32 v157, v62, v62
	v_mul_f32_e32 v159, v63, v63
	s_waitcnt vmcnt(10)
	v_pk_fma_f32 v[58:59], v[224:225], s[88:89], v[58:59] op_sel_hi:[1,0,1]
	v_pk_fma_f32 v[56:57], v[222:223], s[88:89], v[56:57] op_sel_hi:[1,0,1]
	v_mul_f32_e32 v142, v58, v58
	v_pk_fma_f32 v[160:161], v[58:59], v[58:59], v[142:143] op_sel_hi:[1,1,0]
	v_mul_f32_e32 v149, v56, v56
	v_mul_f32_e32 v151, v57, v57
	v_mov_b32_e32 v152, v56
	v_mov_b32_e32 v154, v57
	v_mov_b32_e32 v156, v58
	v_mov_b32_e32 v158, v59
	v_pk_add_f32 v[152:153], v[152:153], v[154:155]
	v_pk_add_f32 v[154:155], v[156:157], v[158:159]
	v_pk_add_f32 v[148:149], v[148:149], v[150:151]
	v_mov_b32_e32 v160, v129
	v_pk_add_f32 v[152:153], v[152:153], v[154:155]
	v_pk_add_f32 v[148:149], v[148:149], v[160:161]
	s_waitcnt vmcnt(9)
	v_pk_fma_f32 v[54:55], v[228:229], s[88:89], v[54:55] op_sel_hi:[1,0,1]
	v_pk_fma_f32 v[52:53], v[226:227], s[88:89], v[52:53] op_sel_hi:[1,0,1]
	v_mul_f32_e32 v163, v52, v52
	v_mul_f32_e32 v165, v53, v53
	v_mul_f32_e32 v167, v54, v54
	v_mul_f32_e32 v169, v55, v55
	v_mov_b32_e32 v162, v52
	v_mov_b32_e32 v164, v53
	v_mov_b32_e32 v166, v54
	v_mov_b32_e32 v168, v55
	v_pk_add_f32 v[148:149], v[152:153], v[148:149]
	v_pk_add_f32 v[150:151], v[162:163], v[164:165]
	v_pk_add_f32 v[152:153], v[166:167], v[168:169]
	s_waitcnt vmcnt(8)
	v_pk_fma_f32 v[50:51], v[232:233], s[88:89], v[50:51] op_sel_hi:[1,0,1]
	v_pk_fma_f32 v[48:49], v[230:231], s[88:89], v[48:49] op_sel_hi:[1,0,1]
	s_mov_b32 s98, 0x160000
	s_mov_b32 s99, 0
	v_lshl_add_u64 v[254:255], v[252:253], 0, s[98:99]
	global_load_dwordx4 v[218:221], v[254:255], off
	global_load_dwordx4 v[222:225], v[254:255], off offset:64
	global_load_dwordx4 v[226:229], v[254:255], off offset:512
	global_load_dwordx4 v[230:233], v[254:255], off offset:576
	v_mul_f32_e32 v171, v50, v50
	v_mul_f32_e32 v143, v48, v48
	v_mul_f32_e32 v145, v49, v49
	v_mul_f32_e32 v173, v51, v51
	v_mov_b32_e32 v142, v48
	v_mov_b32_e32 v144, v49
	v_mov_b32_e32 v170, v50
	v_mov_b32_e32 v172, v51
	v_pk_add_f32 v[150:151], v[150:151], v[152:153]
	v_pk_add_f32 v[142:143], v[142:143], v[144:145]
	v_pk_add_f32 v[144:145], v[170:171], v[172:173]
	v_pk_add_f32 v[148:149], v[148:149], v[150:151]
	v_pk_add_f32 v[142:143], v[142:143], v[144:145]
	s_nop 0
	v_pk_add_f32 v[142:143], v[148:149], v[142:143]
	ds_bpermute_b32 v144, v186, v142
	ds_bpermute_b32 v145, v186, v143
	s_waitcnt lgkmcnt(0)
	v_pk_add_f32 v[142:143], v[142:143], v[144:145]
	ds_bpermute_b32 v144, v185, v142
	ds_bpermute_b32 v145, v185, v143
	s_and_saveexec_b64 s[0:1], vcc
	s_cbranch_execz .LBB0_2076
	s_waitcnt lgkmcnt(0)
	v_pk_add_f32 v[142:143], v[142:143], v[144:145]
	v_lshl_add_u32 v144, v146, 5, s12
	ds_write_b64 v144, v[142:143]
.LBB0_2076:
	s_or_b64 exec, exec, s[0:1]
	v_add_u32_e32 v142, 0x90, v128
	v_ashrrev_i32_e32 v143, 31, v142
	v_lshlrev_b64 v[142:143], 13, v[142:143]
	v_lshl_add_u64 v[142:143], s[68:69], 0, v[142:143]
	v_lshl_add_u64 v[142:143], v[132:133], 2, v[142:143]
	s_waitcnt lgkmcnt(0)
	s_waitcnt vmcnt(11)
	v_pk_fma_f32 v[46:47], v[236:237], s[88:89], v[46:47] op_sel_hi:[1,0,1]
	v_pk_fma_f32 v[44:45], v[234:235], s[88:89], v[44:45] op_sel_hi:[1,0,1]
	v_add_f32_e32 v148, v44, v45
	v_add_f32_e32 v150, v46, v47
	v_mul_f32_e32 v153, v44, v44
	v_mul_f32_e32 v155, v45, v45
	v_mul_f32_e32 v157, v46, v46
	v_mul_f32_e32 v159, v47, v47
	s_waitcnt vmcnt(10)
	v_pk_fma_f32 v[42:43], v[240:241], s[88:89], v[42:43] op_sel_hi:[1,0,1]
	v_pk_fma_f32 v[40:41], v[238:239], s[88:89], v[40:41] op_sel_hi:[1,0,1]
	v_mul_f32_e32 v144, v42, v42
	v_pk_fma_f32 v[160:161], v[42:43], v[42:43], v[144:145] op_sel_hi:[1,1,0]
	v_mul_f32_e32 v149, v40, v40
	v_mul_f32_e32 v151, v41, v41
	v_mov_b32_e32 v152, v40
	v_mov_b32_e32 v154, v41
	v_mov_b32_e32 v156, v42
	v_mov_b32_e32 v158, v43
	v_pk_add_f32 v[152:153], v[152:153], v[154:155]
	v_pk_add_f32 v[154:155], v[156:157], v[158:159]
	v_pk_add_f32 v[148:149], v[148:149], v[150:151]
	v_mov_b32_e32 v160, v129
	v_pk_add_f32 v[152:153], v[152:153], v[154:155]
	v_pk_add_f32 v[148:149], v[148:149], v[160:161]
	s_waitcnt vmcnt(9)
	v_pk_fma_f32 v[38:39], v[244:245], s[88:89], v[38:39] op_sel_hi:[1,0,1]
	v_pk_fma_f32 v[36:37], v[242:243], s[88:89], v[36:37] op_sel_hi:[1,0,1]
	v_mul_f32_e32 v163, v36, v36
	v_mul_f32_e32 v165, v37, v37
	v_mul_f32_e32 v167, v38, v38
	v_mul_f32_e32 v169, v39, v39
	v_mov_b32_e32 v162, v36
	v_mov_b32_e32 v164, v37
	v_mov_b32_e32 v166, v38
	v_mov_b32_e32 v168, v39
	v_pk_add_f32 v[148:149], v[152:153], v[148:149]
	v_pk_add_f32 v[150:151], v[162:163], v[164:165]
	v_pk_add_f32 v[152:153], v[166:167], v[168:169]
	s_waitcnt vmcnt(8)
	v_pk_fma_f32 v[34:35], v[248:249], s[88:89], v[34:35] op_sel_hi:[1,0,1]
	v_pk_fma_f32 v[32:33], v[246:247], s[88:89], v[32:33] op_sel_hi:[1,0,1]
	v_mul_f32_e32 v171, v34, v34
	v_mul_f32_e32 v145, v32, v32
	v_mul_f32_e32 v147, v33, v33
	v_mul_f32_e32 v173, v35, v35
	v_mov_b32_e32 v144, v32
	v_mov_b32_e32 v146, v33
	v_mov_b32_e32 v170, v34
	v_mov_b32_e32 v172, v35
	v_pk_add_f32 v[150:151], v[150:151], v[152:153]
	v_pk_add_f32 v[144:145], v[144:145], v[146:147]
	v_pk_add_f32 v[146:147], v[170:171], v[172:173]
	v_pk_add_f32 v[148:149], v[148:149], v[150:151]
	v_pk_add_f32 v[144:145], v[144:145], v[146:147]
	s_nop 0
	v_pk_add_f32 v[144:145], v[148:149], v[144:145]
	ds_bpermute_b32 v146, v186, v144
	ds_bpermute_b32 v147, v186, v145
	s_waitcnt lgkmcnt(0)
	v_pk_add_f32 v[144:145], v[144:145], v[146:147]
	ds_bpermute_b32 v146, v185, v144
	ds_bpermute_b32 v147, v185, v145
	s_and_saveexec_b64 s[0:1], vcc
	s_cbranch_execz .LBB0_2078
	s_waitcnt lgkmcnt(0)
	v_pk_add_f32 v[144:145], v[144:145], v[146:147]
	ds_write_b64 v187, v[144:145] offset:4608
.LBB0_2078:
	s_or_b64 exec, exec, s[0:1]
	v_add_u32_e32 v144, 0xa0, v128
	v_ashrrev_i32_e32 v145, 31, v144
	v_lshlrev_b64 v[144:145], 13, v[144:145]
	v_lshl_add_u64 v[144:145], s[68:69], 0, v[144:145]
	v_lshl_add_u64 v[144:145], v[132:133], 2, v[144:145]
	s_waitcnt lgkmcnt(0)
	s_waitcnt vmcnt(7)
	v_pk_fma_f32 v[148:149], v[204:205], s[88:89], v[30:31] op_sel_hi:[1,0,1]
	v_pk_fma_f32 v[146:147], v[202:203], s[88:89], v[28:29] op_sel_hi:[1,0,1]
	v_add_f32_e32 v162, v146, v147
	v_add_f32_e32 v164, v148, v149
	v_mul_f32_e32 v167, v146, v146
	v_mul_f32_e32 v169, v147, v147
	v_mul_f32_e32 v171, v148, v148
	v_mul_f32_e32 v173, v149, v149
	s_waitcnt vmcnt(6)
	v_pk_fma_f32 v[152:153], v[208:209], s[88:89], v[26:27] op_sel_hi:[1,0,1]
	v_pk_fma_f32 v[150:151], v[206:207], s[88:89], v[24:25] op_sel_hi:[1,0,1]
	v_mul_f32_e32 v24, v152, v152
	v_pk_fma_f32 v[28:29], v[152:153], v[152:153], v[24:25] op_sel_hi:[1,1,0]
	v_mul_f32_e32 v163, v150, v150
	v_mul_f32_e32 v165, v151, v151
	v_mov_b32_e32 v166, v150
	v_mov_b32_e32 v168, v151
	v_mov_b32_e32 v170, v152
	v_mov_b32_e32 v172, v153
	v_pk_add_f32 v[166:167], v[166:167], v[168:169]
	v_pk_add_f32 v[168:169], v[170:171], v[172:173]
	v_pk_add_f32 v[162:163], v[162:163], v[164:165]
	v_mov_b32_e32 v28, v129
	v_pk_add_f32 v[166:167], v[166:167], v[168:169]
	v_pk_add_f32 v[28:29], v[162:163], v[28:29]
	s_waitcnt vmcnt(5)
	v_pk_fma_f32 v[156:157], v[212:213], s[88:89], v[22:23] op_sel_hi:[1,0,1]
	v_pk_fma_f32 v[154:155], v[210:211], s[88:89], v[20:21] op_sel_hi:[1,0,1]
	v_mul_f32_e32 v25, v154, v154
	v_mul_f32_e32 v27, v155, v155
	v_mul_f32_e32 v31, v156, v156
	v_mul_f32_e32 v175, v157, v157
	v_mov_b32_e32 v24, v154
	v_mov_b32_e32 v26, v155
	v_mov_b32_e32 v30, v156
	v_mov_b32_e32 v174, v157
	v_pk_add_f32 v[24:25], v[24:25], v[26:27]
	v_pk_add_f32 v[26:27], v[30:31], v[174:175]
	v_pk_add_f32 v[28:29], v[166:167], v[28:29]
	v_pk_add_f32 v[24:25], v[24:25], v[26:27]
	s_waitcnt vmcnt(4)
	v_pk_fma_f32 v[160:161], v[216:217], s[88:89], v[18:19] op_sel_hi:[1,0,1]
	v_pk_fma_f32 v[158:159], v[214:215], s[88:89], v[16:17] op_sel_hi:[1,0,1]
	v_mul_f32_e32 v21, v160, v160
	v_mul_f32_e32 v17, v158, v158
	v_mul_f32_e32 v19, v159, v159
	v_mul_f32_e32 v23, v161, v161
	v_mov_b32_e32 v16, v158
	v_mov_b32_e32 v18, v159
	v_mov_b32_e32 v20, v160
	v_mov_b32_e32 v22, v161
	v_pk_add_f32 v[16:17], v[16:17], v[18:19]
	v_pk_add_f32 v[18:19], v[20:21], v[22:23]
	v_pk_add_f32 v[24:25], v[28:29], v[24:25]
	v_pk_add_f32 v[16:17], v[16:17], v[18:19]
	s_nop 0
	v_pk_add_f32 v[16:17], v[24:25], v[16:17]
	ds_bpermute_b32 v18, v186, v16
	ds_bpermute_b32 v19, v186, v17
	s_waitcnt lgkmcnt(0)
	v_pk_add_f32 v[16:17], v[16:17], v[18:19]
	ds_bpermute_b32 v18, v185, v16
	ds_bpermute_b32 v19, v185, v17
	s_and_saveexec_b64 s[0:1], vcc
	s_cbranch_execz .LBB0_2080
	s_waitcnt lgkmcnt(0)
	v_pk_add_f32 v[16:17], v[16:17], v[18:19]
	ds_write_b64 v187, v[16:17] offset:5120
.LBB0_2080:
	s_or_b64 exec, exec, s[0:1]
	v_add_u32_e32 v16, 0xb0, v128
	v_ashrrev_i32_e32 v17, 31, v16
	v_lshlrev_b64 v[16:17], 13, v[16:17]
	v_lshl_add_u64 v[16:17], s[68:69], 0, v[16:17]
	v_lshl_add_u64 v[162:163], v[132:133], 2, v[16:17]
	s_waitcnt lgkmcnt(0)
	s_waitcnt vmcnt(3)
	v_pk_fma_f32 v[166:167], v[220:221], s[88:89], v[14:15] op_sel_hi:[1,0,1]
	v_pk_fma_f32 v[164:165], v[218:219], s[88:89], v[12:13] op_sel_hi:[1,0,1]
	v_add_f32_e32 v16, v164, v165
	v_add_f32_e32 v18, v166, v167
	v_mul_f32_e32 v21, v164, v164
	v_mul_f32_e32 v23, v165, v165
	v_mul_f32_e32 v25, v166, v166
	v_mul_f32_e32 v27, v167, v167
	s_waitcnt vmcnt(2)
	v_pk_fma_f32 v[170:171], v[224:225], s[88:89], v[10:11] op_sel_hi:[1,0,1]
	v_pk_fma_f32 v[168:169], v[222:223], s[88:89], v[8:9] op_sel_hi:[1,0,1]
	v_mul_f32_e32 v8, v170, v170
	v_pk_fma_f32 v[12:13], v[170:171], v[170:171], v[8:9] op_sel_hi:[1,1,0]
	v_mul_f32_e32 v17, v168, v168
	v_mul_f32_e32 v19, v169, v169
	v_mov_b32_e32 v20, v168
	v_mov_b32_e32 v22, v169
	v_mov_b32_e32 v24, v170
	v_mov_b32_e32 v26, v171
	v_pk_add_f32 v[20:21], v[20:21], v[22:23]
	v_pk_add_f32 v[22:23], v[24:25], v[26:27]
	v_pk_add_f32 v[16:17], v[16:17], v[18:19]
	v_mov_b32_e32 v12, v129
	v_pk_add_f32 v[20:21], v[20:21], v[22:23]
	v_pk_add_f32 v[12:13], v[16:17], v[12:13]
	s_waitcnt vmcnt(1)
	v_pk_fma_f32 v[174:175], v[228:229], s[88:89], v[6:7] op_sel_hi:[1,0,1]
	v_pk_fma_f32 v[172:173], v[226:227], s[88:89], v[4:5] op_sel_hi:[1,0,1]
	v_mul_f32_e32 v9, v172, v172
	v_mul_f32_e32 v11, v173, v173
	v_mul_f32_e32 v15, v174, v174
	v_mul_f32_e32 v29, v175, v175
	v_mov_b32_e32 v8, v172
	v_mov_b32_e32 v10, v173
	v_mov_b32_e32 v14, v174
	v_mov_b32_e32 v28, v175
	v_pk_add_f32 v[8:9], v[8:9], v[10:11]
	v_pk_add_f32 v[10:11], v[14:15], v[28:29]
	v_pk_add_f32 v[12:13], v[20:21], v[12:13]
	v_pk_add_f32 v[8:9], v[8:9], v[10:11]
	s_waitcnt vmcnt(0)
	v_pk_fma_f32 v[178:179], v[232:233], s[88:89], v[2:3] op_sel_hi:[1,0,1]
	v_pk_fma_f32 v[176:177], v[230:231], s[88:89], v[0:1] op_sel_hi:[1,0,1]
	v_mul_f32_e32 v5, v178, v178
	v_mul_f32_e32 v1, v176, v176
	v_mul_f32_e32 v3, v177, v177
	v_mul_f32_e32 v7, v179, v179
	v_mov_b32_e32 v0, v176
	v_mov_b32_e32 v2, v177
	v_mov_b32_e32 v4, v178
	v_mov_b32_e32 v6, v179
	v_pk_add_f32 v[0:1], v[0:1], v[2:3]
	v_pk_add_f32 v[2:3], v[4:5], v[6:7]
	v_pk_add_f32 v[8:9], v[12:13], v[8:9]
	v_pk_add_f32 v[0:1], v[0:1], v[2:3]
	s_nop 0
	v_pk_add_f32 v[0:1], v[8:9], v[0:1]
	ds_bpermute_b32 v2, v186, v0
	ds_bpermute_b32 v3, v186, v1
	s_waitcnt lgkmcnt(0)
	v_pk_add_f32 v[0:1], v[0:1], v[2:3]
	ds_bpermute_b32 v2, v185, v0
	ds_bpermute_b32 v3, v185, v1
	s_and_saveexec_b64 s[0:1], vcc
	s_cbranch_execz .LBB0_2082
	s_waitcnt lgkmcnt(0)
	v_pk_add_f32 v[0:1], v[0:1], v[2:3]
	ds_write_b64 v187, v[0:1] offset:5632

	.amdhsa_kernel _Z8mega_fwd4Args
		.amdhsa_group_segment_fixed_size 0
		.amdhsa_private_segment_fixed_size 0
		.amdhsa_kernarg_size 424
		.amdhsa_user_sgpr_count 2
		.amdhsa_user_sgpr_dispatch_ptr 0
		.amdhsa_user_sgpr_queue_ptr 0
		.amdhsa_user_sgpr_kernarg_segment_ptr 1
		.amdhsa_user_sgpr_dispatch_id 0
		.amdhsa_user_sgpr_kernarg_preload_length 0
		.amdhsa_user_sgpr_kernarg_preload_offset 0
		.amdhsa_user_sgpr_private_segment_size 0
		.amdhsa_uses_dynamic_stack 0
		.amdhsa_enable_private_segment 0
		.amdhsa_system_sgpr_workgroup_id_x 1
		.amdhsa_system_sgpr_workgroup_id_y 0
		.amdhsa_system_sgpr_workgroup_id_z 0
		.amdhsa_system_sgpr_workgroup_info 0
		.amdhsa_system_vgpr_workitem_id 2
		.amdhsa_next_free_vgpr 256
		.amdhsa_next_free_sgpr 101
		.amdhsa_accum_offset 256
		.amdhsa_reserve_vcc 1
		.amdhsa_float_round_mode_32 0
		.amdhsa_float_round_mode_16_64 0
		.amdhsa_float_denorm_mode_32 3
		.amdhsa_float_denorm_mode_16_64 3
		.amdhsa_dx10_clamp 1
		.amdhsa_ieee_mode 1
		.amdhsa_fp16_overflow 0
		.amdhsa_tg_split 0
		.amdhsa_exception_fp_ieee_invalid_op 0
		.amdhsa_exception_fp_denorm_src 0
		.amdhsa_exception_fp_ieee_div_zero 0
		.amdhsa_exception_fp_ieee_overflow 0
		.amdhsa_exception_fp_ieee_underflow 0
		.amdhsa_exception_fp_ieee_inexact 0
		.amdhsa_exception_int_div_zero 0
	.end_amdhsa_kernel

amdhsa.kernels:
  - .agpr_count:     0
    .args:
      - .offset:         0
        .size:           168
        .value_kind:     by_value
      - .offset:         168
        .size:           4
        .value_kind:     hidden_block_count_x
      - .offset:         172
        .size:           4
        .value_kind:     hidden_block_count_y
      - .offset:         176
        .size:           4
        .value_kind:     hidden_block_count_z
      - .offset:         180
        .size:           2
        .value_kind:     hidden_group_size_x
      - .offset:         182
        .size:           2
        .value_kind:     hidden_group_size_y
      - .offset:         184
        .size:           2
        .value_kind:     hidden_group_size_z
      - .offset:         186
        .size:           2
        .value_kind:     hidden_remainder_x
      - .offset:         188
        .size:           2
        .value_kind:     hidden_remainder_y
      - .offset:         190
        .size:           2
        .value_kind:     hidden_remainder_z
      - .offset:         208
        .size:           8
        .value_kind:     hidden_global_offset_x
      - .offset:         216
        .size:           8
        .value_kind:     hidden_global_offset_y
      - .offset:         224
        .size:           8
        .value_kind:     hidden_global_offset_z
      - .offset:         232
        .size:           2
        .value_kind:     hidden_grid_dims
      - .offset:         256
        .size:           8
        .value_kind:     hidden_multigrid_sync_arg
      - .offset:         288
        .size:           4
        .value_kind:     hidden_dynamic_lds_size
    .group_segment_fixed_size: 0
    .kernarg_segment_align: 8
    .kernarg_segment_size: 424
    .language:       OpenCL C
    .language_version:
      - 2
      - 0
    .max_flat_workgroup_size: 512
    .name:           _Z8mega_fwd4Args
    .private_segment_fixed_size: 0
    .sgpr_count:     107
    .sgpr_spill_count: 175
    .symbol:         _Z8mega_fwd4Args.kd
    .uniform_work_group_size: 1
    .uses_dynamic_stack: false
    .vgpr_count:     256
    .vgpr_spill_count: 0
    .wavefront_size: 64
